# GEMM K-loops: reorder MFMAs so the two k-steps of each accumulator are adjacent (same math order per accumulator; C forwarded instead of re-read)
# speedup vs baseline: 1.0091x; 1.0079x over previous
.LBB0_261:
	s_add_u32 s0, s76, 0xfff80080
	s_addc_u32 s1, s77, -1
	s_and_b64 s[84:85], s[84:85], exec
	s_cselect_b32 vcc_hi, s22, s1
	s_cselect_b32 vcc_lo, s23, s0
	s_cselect_b32 s85, s49, s58
	s_cselect_b32 s84, s57, s51
	s_add_i32 s0, 0, 0x10000
	s_add_i32 s1, 0, 0x14000
	v_add_u32_e32 v158, s0, v176
	v_add_u32_e32 v174, s1, v176
	ds_read_b128 v[146:149], v158
	ds_read_b128 v[150:153], v158 offset:1024
	ds_read_b128 v[154:157], v158 offset:2048
	ds_read_b128 v[158:161], v158 offset:3072
	ds_read_b128 v[162:165], v174
	ds_read_b128 v[166:169], v174 offset:1024
	ds_read_b128 v[170:173], v174 offset:2048
	ds_read_b128 v[178:181], v174 offset:3072
	v_lshl_add_u64 v[174:175], s[76:77], 0, v[138:139]
	s_add_i32 m0, s21, 0xc000
	ds_read_b128 v[182:185], v177
	ds_read_b128 v[186:189], v177 offset:1024
	ds_read_b128 v[190:193], v177 offset:2048
	ds_read_b128 v[204:207], v177 offset:3072
	ds_read_b128 v[208:211], v177 offset:4096
	ds_read_b128 v[212:215], v177 offset:5120
	ds_read_b128 v[216:219], v177 offset:6144
	ds_read_b128 v[220:223], v177 offset:7168
	global_load_lds_dwordx4 v[174:175], off
	v_lshl_add_u64 v[174:175], s[76:77], 0, v[140:141]
	s_add_i32 m0, s21, 0xe000
	s_nop 0
	global_load_lds_dwordx4 v[174:175], off
	s_waitcnt vmcnt(8)
	s_waitcnt lgkmcnt(0)
	s_barrier
	s_setprio 1
	s_waitcnt lgkmcnt(0)
	v_mfma_f32_16x16x32_bf16 v[126:129], v[146:149], v[182:185], v[126:129]
	v_mfma_f32_16x16x32_bf16 v[126:129], v[150:153], v[186:189], v[126:129]
	v_mfma_f32_16x16x32_bf16 v[122:125], v[154:157], v[182:185], v[122:125]
	v_mfma_f32_16x16x32_bf16 v[122:125], v[158:161], v[186:189], v[122:125]
	v_mfma_f32_16x16x32_bf16 v[110:113], v[146:149], v[190:193], v[110:113]
	v_mfma_f32_16x16x32_bf16 v[110:113], v[150:153], v[204:207], v[110:113]
	v_mfma_f32_16x16x32_bf16 v[106:109], v[154:157], v[190:193], v[106:109]
	v_mfma_f32_16x16x32_bf16 v[106:109], v[158:161], v[204:207], v[106:109]
	v_mfma_f32_16x16x32_bf16 v[94:97], v[146:149], v[208:211], v[94:97]
	v_mfma_f32_16x16x32_bf16 v[94:97], v[150:153], v[212:215], v[94:97]
	v_mfma_f32_16x16x32_bf16 v[90:93], v[154:157], v[208:211], v[90:93]
	v_mfma_f32_16x16x32_bf16 v[90:93], v[158:161], v[212:215], v[90:93]
	v_mfma_f32_16x16x32_bf16 v[78:81], v[146:149], v[216:219], v[78:81]
	v_mfma_f32_16x16x32_bf16 v[78:81], v[150:153], v[220:223], v[78:81]
	v_mfma_f32_16x16x32_bf16 v[74:77], v[154:157], v[216:219], v[74:77]
	v_mfma_f32_16x16x32_bf16 v[74:77], v[158:161], v[220:223], v[74:77]
	s_setprio 0
	s_setprio 1
	v_mfma_f32_16x16x32_bf16 v[118:121], v[162:165], v[182:185], v[118:121]
	v_mfma_f32_16x16x32_bf16 v[118:121], v[166:169], v[186:189], v[118:121]
	v_mfma_f32_16x16x32_bf16 v[114:117], v[170:173], v[182:185], v[114:117]
	v_mfma_f32_16x16x32_bf16 v[114:117], v[178:181], v[186:189], v[114:117]
	v_mfma_f32_16x16x32_bf16 v[102:105], v[162:165], v[190:193], v[102:105]
	v_mfma_f32_16x16x32_bf16 v[102:105], v[166:169], v[204:207], v[102:105]
	v_mfma_f32_16x16x32_bf16 v[98:101], v[170:173], v[190:193], v[98:101]
	v_mfma_f32_16x16x32_bf16 v[98:101], v[178:181], v[204:207], v[98:101]
	v_mfma_f32_16x16x32_bf16 v[86:89], v[162:165], v[208:211], v[86:89]
	v_mfma_f32_16x16x32_bf16 v[86:89], v[166:169], v[212:215], v[86:89]
	v_mfma_f32_16x16x32_bf16 v[82:85], v[170:173], v[208:211], v[82:85]
	v_mfma_f32_16x16x32_bf16 v[82:85], v[178:181], v[212:215], v[82:85]
	v_mfma_f32_16x16x32_bf16 v[70:73], v[162:165], v[216:219], v[70:73]
	v_mfma_f32_16x16x32_bf16 v[70:73], v[166:169], v[220:223], v[70:73]
	v_mfma_f32_16x16x32_bf16 v[66:69], v[170:173], v[216:219], v[66:69]
	v_mfma_f32_16x16x32_bf16 v[66:69], v[178:181], v[220:223], v[66:69]
	s_setprio 0
	s_barrier
	s_add_i32 s0, s0, s20
	v_lshl_add_u64 v[174:175], s[84:85], 0, v[132:133]
	s_mov_b32 m0, s0
	ds_read_b128 v[182:185], v177 offset:16384
	ds_read_b128 v[186:189], v177 offset:17408
	ds_read_b128 v[190:193], v177 offset:18432
	ds_read_b128 v[204:207], v177 offset:19456
	ds_read_b128 v[208:211], v177 offset:20480
	ds_read_b128 v[212:215], v177 offset:21504
	ds_read_b128 v[216:219], v177 offset:22528
	ds_read_b128 v[220:223], v177 offset:23552
	global_load_lds_dwordx4 v[174:175], off
	s_add_i32 m0, s0, 0x2000
	s_add_u32 s94, s84, 0x80000
	v_lshl_add_u64 v[224:225], s[84:85], 0, v[130:131]
	s_addc_u32 s95, s85, 0
	s_add_i32 s0, s1, s20
	global_load_lds_dwordx4 v[224:225], off
	v_lshl_add_u64 v[226:227], s[94:95], 0, v[132:133]
	s_mov_b32 m0, s0
	v_lshl_add_u64 v[228:229], vcc, 0, v[130:131]
	global_load_lds_dwordx4 v[226:227], off
	v_lshl_add_u64 v[226:227], s[94:95], 0, v[130:131]
	s_add_i32 m0, s0, 0x2000
	s_nop 0
	global_load_lds_dwordx4 v[226:227], off
	v_lshl_add_u64 v[226:227], vcc, 0, v[132:133]
	s_mov_b32 m0, s21
	s_nop 0
	global_load_lds_dwordx4 v[226:227], off
	s_mov_b32 m0, s26
	s_nop 0
	global_load_lds_dwordx4 v[228:229], off
	s_waitcnt vmcnt(8)
	s_waitcnt lgkmcnt(0)
	s_barrier
	s_setprio 1
	s_waitcnt lgkmcnt(0)
	v_mfma_f32_16x16x32_bf16 v[62:65], v[146:149], v[182:185], v[62:65]
	v_mfma_f32_16x16x32_bf16 v[62:65], v[150:153], v[186:189], v[62:65]
	v_mfma_f32_16x16x32_bf16 v[58:61], v[154:157], v[182:185], v[58:61]
	v_mfma_f32_16x16x32_bf16 v[58:61], v[158:161], v[186:189], v[58:61]
	v_mfma_f32_16x16x32_bf16 v[46:49], v[146:149], v[190:193], v[46:49]
	v_mfma_f32_16x16x32_bf16 v[46:49], v[150:153], v[204:207], v[46:49]
	v_mfma_f32_16x16x32_bf16 v[42:45], v[154:157], v[190:193], v[42:45]
	v_mfma_f32_16x16x32_bf16 v[42:45], v[158:161], v[204:207], v[42:45]
	v_mfma_f32_16x16x32_bf16 v[30:33], v[146:149], v[208:211], v[30:33]
	v_mfma_f32_16x16x32_bf16 v[30:33], v[150:153], v[212:215], v[30:33]
	v_mfma_f32_16x16x32_bf16 v[26:29], v[154:157], v[208:211], v[26:29]
	v_mfma_f32_16x16x32_bf16 v[26:29], v[158:161], v[212:215], v[26:29]
	v_mfma_f32_16x16x32_bf16 v[14:17], v[146:149], v[216:219], v[14:17]
	v_mfma_f32_16x16x32_bf16 v[14:17], v[150:153], v[220:223], v[14:17]
	v_mfma_f32_16x16x32_bf16 v[10:13], v[154:157], v[216:219], v[10:13]
	v_mfma_f32_16x16x32_bf16 v[10:13], v[158:161], v[220:223], v[10:13]
	s_setprio 0
	s_setprio 1
	v_mfma_f32_16x16x32_bf16 v[54:57], v[162:165], v[182:185], v[54:57]
	v_mfma_f32_16x16x32_bf16 v[54:57], v[166:169], v[186:189], v[54:57]
	v_mfma_f32_16x16x32_bf16 v[50:53], v[170:173], v[182:185], v[50:53]
	v_mfma_f32_16x16x32_bf16 v[50:53], v[178:181], v[186:189], v[50:53]
	v_mfma_f32_16x16x32_bf16 v[38:41], v[162:165], v[190:193], v[38:41]
	v_mfma_f32_16x16x32_bf16 v[38:41], v[166:169], v[204:207], v[38:41]
	v_mfma_f32_16x16x32_bf16 v[34:37], v[170:173], v[190:193], v[34:37]
	v_mfma_f32_16x16x32_bf16 v[34:37], v[178:181], v[204:207], v[34:37]
	v_mfma_f32_16x16x32_bf16 v[22:25], v[162:165], v[208:211], v[22:25]
	v_mfma_f32_16x16x32_bf16 v[22:25], v[166:169], v[212:215], v[22:25]
	v_mfma_f32_16x16x32_bf16 v[18:21], v[170:173], v[208:211], v[18:21]
	v_mfma_f32_16x16x32_bf16 v[18:21], v[178:181], v[212:215], v[18:21]
	v_mfma_f32_16x16x32_bf16 v[6:9], v[162:165], v[216:219], v[6:9]
	v_mfma_f32_16x16x32_bf16 v[6:9], v[166:169], v[220:223], v[6:9]
	v_mfma_f32_16x16x32_bf16 v[2:5], v[170:173], v[216:219], v[2:5]
	v_mfma_f32_16x16x32_bf16 v[2:5], v[178:181], v[220:223], v[2:5]
	s_setprio 0
	s_barrier
	s_add_i32 s0, 0, 0x18000
	s_add_i32 s1, 0, 0x1c000
	v_add_u32_e32 v158, s0, v176
	v_add_u32_e32 v178, s1, v176
	ds_read_b128 v[146:149], v158
	ds_read_b128 v[150:153], v158 offset:1024
	ds_read_b128 v[154:157], v158 offset:2048
	ds_read_b128 v[158:161], v158 offset:3072
	ds_read_b128 v[162:165], v178
	ds_read_b128 v[166:169], v178 offset:1024
	ds_read_b128 v[170:173], v178 offset:2048
	ds_read_b128 v[178:181], v178 offset:3072
	s_add_u32 s94, vcc_lo, 0x80000
	s_addc_u32 s95, vcc_hi, 0
	s_mov_b32 m0, s27
	v_lshl_add_u64 v[230:231], s[94:95], 0, v[132:133]
	ds_read_b128 v[182:185], v177 offset:32768
	ds_read_b128 v[186:189], v177 offset:33792
	ds_read_b128 v[190:193], v177 offset:34816
	ds_read_b128 v[204:207], v177 offset:35840
	ds_read_b128 v[208:211], v177 offset:36864
	ds_read_b128 v[212:215], v177 offset:37888
	ds_read_b128 v[216:219], v177 offset:38912
	ds_read_b128 v[220:223], v177 offset:39936
	global_load_lds_dwordx4 v[230:231], off
	v_lshl_add_u64 v[230:231], s[94:95], 0, v[130:131]
	s_mov_b32 m0, s29
	s_nop 0
	global_load_lds_dwordx4 v[230:231], off
	s_waitcnt vmcnt(8)
	s_waitcnt lgkmcnt(0)
	s_barrier
	s_setprio 1
	s_waitcnt lgkmcnt(0)
	v_mfma_f32_16x16x32_bf16 v[126:129], v[146:149], v[182:185], v[126:129]
	v_mfma_f32_16x16x32_bf16 v[126:129], v[150:153], v[186:189], v[126:129]
	v_mfma_f32_16x16x32_bf16 v[122:125], v[154:157], v[182:185], v[122:125]
	v_mfma_f32_16x16x32_bf16 v[122:125], v[158:161], v[186:189], v[122:125]
	v_mfma_f32_16x16x32_bf16 v[110:113], v[146:149], v[190:193], v[110:113]
	v_mfma_f32_16x16x32_bf16 v[110:113], v[150:153], v[204:207], v[110:113]
	v_mfma_f32_16x16x32_bf16 v[106:109], v[154:157], v[190:193], v[106:109]
	v_mfma_f32_16x16x32_bf16 v[106:109], v[158:161], v[204:207], v[106:109]
	v_mfma_f32_16x16x32_bf16 v[94:97], v[146:149], v[208:211], v[94:97]
	v_mfma_f32_16x16x32_bf16 v[94:97], v[150:153], v[212:215], v[94:97]
	v_mfma_f32_16x16x32_bf16 v[90:93], v[154:157], v[208:211], v[90:93]
	v_mfma_f32_16x16x32_bf16 v[90:93], v[158:161], v[212:215], v[90:93]
	v_mfma_f32_16x16x32_bf16 v[78:81], v[146:149], v[216:219], v[78:81]
	v_mfma_f32_16x16x32_bf16 v[78:81], v[150:153], v[220:223], v[78:81]
	v_mfma_f32_16x16x32_bf16 v[74:77], v[154:157], v[216:219], v[74:77]
	v_mfma_f32_16x16x32_bf16 v[74:77], v[158:161], v[220:223], v[74:77]
	s_setprio 0
	s_setprio 1
	v_mfma_f32_16x16x32_bf16 v[118:121], v[162:165], v[182:185], v[118:121]
	v_mfma_f32_16x16x32_bf16 v[118:121], v[166:169], v[186:189], v[118:121]
	v_mfma_f32_16x16x32_bf16 v[114:117], v[170:173], v[182:185], v[114:117]
	v_mfma_f32_16x16x32_bf16 v[114:117], v[178:181], v[186:189], v[114:117]
	v_mfma_f32_16x16x32_bf16 v[102:105], v[162:165], v[190:193], v[102:105]
	v_mfma_f32_16x16x32_bf16 v[102:105], v[166:169], v[204:207], v[102:105]
	v_mfma_f32_16x16x32_bf16 v[98:101], v[170:173], v[190:193], v[98:101]
	v_mfma_f32_16x16x32_bf16 v[98:101], v[178:181], v[204:207], v[98:101]
	v_mfma_f32_16x16x32_bf16 v[86:89], v[162:165], v[208:211], v[86:89]
	v_mfma_f32_16x16x32_bf16 v[86:89], v[166:169], v[212:215], v[86:89]
	v_mfma_f32_16x16x32_bf16 v[82:85], v[170:173], v[208:211], v[82:85]
	v_mfma_f32_16x16x32_bf16 v[82:85], v[178:181], v[212:215], v[82:85]
	v_mfma_f32_16x16x32_bf16 v[70:73], v[162:165], v[216:219], v[70:73]
	v_mfma_f32_16x16x32_bf16 v[70:73], v[166:169], v[220:223], v[70:73]
	v_mfma_f32_16x16x32_bf16 v[66:69], v[170:173], v[216:219], v[66:69]
	v_mfma_f32_16x16x32_bf16 v[66:69], v[178:181], v[220:223], v[66:69]
	s_setprio 0
	s_barrier
	s_add_i32 s0, s0, s20
	v_lshl_add_u64 v[174:175], v[174:175], 0, s[82:83]
	s_mov_b32 m0, s0
	ds_read_b128 v[182:185], v177 offset:49152
	ds_read_b128 v[186:189], v177 offset:50176
	ds_read_b128 v[190:193], v177 offset:51200
	ds_read_b128 v[204:207], v177 offset:52224
	ds_read_b128 v[208:211], v177 offset:53248
	ds_read_b128 v[212:215], v177 offset:54272
	ds_read_b128 v[216:219], v177 offset:55296
	ds_read_b128 v[220:223], v177 offset:56320
	global_load_lds_dwordx4 v[174:175], off
	s_add_i32 m0, s0, 0x2000
	s_add_u32 s84, s84, 0x80080
	v_lshl_add_u64 v[174:175], v[224:225], 0, s[82:83]
	s_addc_u32 s85, s85, 0
	s_add_i32 s0, s1, s20
	global_load_lds_dwordx4 v[174:175], off
	v_lshl_add_u64 v[174:175], s[84:85], 0, v[132:133]
	s_mov_b32 m0, s0
	s_nop 0
	global_load_lds_dwordx4 v[174:175], off
	v_lshl_add_u64 v[174:175], s[84:85], 0, v[130:131]
	s_add_i32 m0, s0, 0x2000
	s_nop 0
	global_load_lds_dwordx4 v[174:175], off
	v_lshl_add_u64 v[174:175], v[226:227], 0, s[82:83]
	s_mov_b32 m0, s40
	s_nop 0
	global_load_lds_dwordx4 v[174:175], off
	v_lshl_add_u64 v[174:175], v[228:229], 0, s[82:83]
	s_mov_b32 m0, s41
	s_nop 0
	global_load_lds_dwordx4 v[174:175], off
	s_waitcnt vmcnt(8)
	s_waitcnt lgkmcnt(0)
	s_barrier
	s_setprio 1
	s_waitcnt lgkmcnt(0)
	v_mfma_f32_16x16x32_bf16 v[62:65], v[146:149], v[182:185], v[62:65]
	v_mfma_f32_16x16x32_bf16 v[62:65], v[150:153], v[186:189], v[62:65]
	v_mfma_f32_16x16x32_bf16 v[58:61], v[154:157], v[182:185], v[58:61]
	v_mfma_f32_16x16x32_bf16 v[58:61], v[158:161], v[186:189], v[58:61]
	v_mfma_f32_16x16x32_bf16 v[46:49], v[146:149], v[190:193], v[46:49]
	v_mfma_f32_16x16x32_bf16 v[46:49], v[150:153], v[204:207], v[46:49]
	v_mfma_f32_16x16x32_bf16 v[42:45], v[154:157], v[190:193], v[42:45]
	v_mfma_f32_16x16x32_bf16 v[42:45], v[158:161], v[204:207], v[42:45]
	v_mfma_f32_16x16x32_bf16 v[30:33], v[146:149], v[208:211], v[30:33]
	v_mfma_f32_16x16x32_bf16 v[30:33], v[150:153], v[212:215], v[30:33]
	v_mfma_f32_16x16x32_bf16 v[26:29], v[154:157], v[208:211], v[26:29]
	v_mfma_f32_16x16x32_bf16 v[26:29], v[158:161], v[212:215], v[26:29]
	v_mfma_f32_16x16x32_bf16 v[14:17], v[146:149], v[216:219], v[14:17]
	v_mfma_f32_16x16x32_bf16 v[14:17], v[150:153], v[220:223], v[14:17]
	v_mfma_f32_16x16x32_bf16 v[10:13], v[154:157], v[216:219], v[10:13]
	v_mfma_f32_16x16x32_bf16 v[10:13], v[158:161], v[220:223], v[10:13]
	s_setprio 0
	s_setprio 1
	v_mfma_f32_16x16x32_bf16 v[54:57], v[162:165], v[182:185], v[54:57]
	v_mfma_f32_16x16x32_bf16 v[54:57], v[166:169], v[186:189], v[54:57]
	v_mfma_f32_16x16x32_bf16 v[50:53], v[170:173], v[182:185], v[50:53]
	v_mfma_f32_16x16x32_bf16 v[50:53], v[178:181], v[186:189], v[50:53]
	v_mfma_f32_16x16x32_bf16 v[38:41], v[162:165], v[190:193], v[38:41]
	v_mfma_f32_16x16x32_bf16 v[38:41], v[166:169], v[204:207], v[38:41]
	v_mfma_f32_16x16x32_bf16 v[34:37], v[170:173], v[190:193], v[34:37]
	v_mfma_f32_16x16x32_bf16 v[34:37], v[178:181], v[204:207], v[34:37]
	v_mfma_f32_16x16x32_bf16 v[22:25], v[162:165], v[208:211], v[22:25]
	v_mfma_f32_16x16x32_bf16 v[22:25], v[166:169], v[212:215], v[22:25]
	v_mfma_f32_16x16x32_bf16 v[18:21], v[170:173], v[208:211], v[18:21]
	v_mfma_f32_16x16x32_bf16 v[18:21], v[178:181], v[212:215], v[18:21]
	v_mfma_f32_16x16x32_bf16 v[6:9], v[162:165], v[216:219], v[6:9]
	v_mfma_f32_16x16x32_bf16 v[6:9], v[166:169], v[220:223], v[6:9]
	v_mfma_f32_16x16x32_bf16 v[2:5], v[170:173], v[216:219], v[2:5]
	v_mfma_f32_16x16x32_bf16 v[2:5], v[178:181], v[220:223], v[2:5]
	s_setprio 0
	s_barrier
	s_add_i32 s65, s65, 2
	s_add_u32 s76, s76, 0x100
	s_addc_u32 s77, s77, 0
	s_add_u32 s51, s51, 0x100
	s_addc_u32 s58, s58, 0
	s_cmp_gt_u32 s65, 29
	s_cbranch_scc1 .LBB0_264

.LBB0_285:
	s_add_u32 s0, s76, 0xfff80080
	s_addc_u32 s1, s77, -1
	s_and_b64 s[70:71], s[70:71], exec
	s_cselect_b32 vcc_hi, s21, s1
	s_cselect_b32 vcc_lo, s22, s0
	s_cselect_b32 s71, s23, s41
	s_cselect_b32 s70, s39, s7
	s_add_i32 s0, 0, 0x10000
	s_add_i32 s1, 0, 0x14000
	v_add_u32_e32 v146, s0, v1
	v_add_u32_e32 v174, s1, v1
	ds_read_b128 v[134:137], v146
	ds_read_b128 v[138:141], v146 offset:1024
	ds_read_b128 v[142:145], v146 offset:2048
	ds_read_b128 v[146:149], v146 offset:3072
	ds_read_b128 v[150:153], v174
	ds_read_b128 v[154:157], v174 offset:1024
	ds_read_b128 v[158:161], v174 offset:2048
	ds_read_b128 v[174:177], v174 offset:3072
	v_lshl_add_u64 v[220:221], s[76:77], 0, v[170:171]
	s_add_i32 m0, s67, 0xc000
	ds_read_b128 v[178:181], v222
	ds_read_b128 v[182:185], v222 offset:1024
	ds_read_b128 v[186:189], v222 offset:2048
	ds_read_b128 v[190:193], v222 offset:3072
	ds_read_b128 v[204:207], v222 offset:4096
	ds_read_b128 v[208:211], v222 offset:5120
	ds_read_b128 v[212:215], v222 offset:6144
	ds_read_b128 v[216:219], v222 offset:7168
	global_load_lds_dwordx4 v[220:221], off
	v_lshl_add_u64 v[220:221], s[76:77], 0, v[172:173]
	s_add_i32 m0, s67, 0xe000
	s_nop 0
	global_load_lds_dwordx4 v[220:221], off
	s_waitcnt vmcnt(8)
	s_waitcnt lgkmcnt(0)
	s_barrier
	s_setprio 1
	s_waitcnt lgkmcnt(0)
	v_mfma_f32_16x16x32_bf16 v[126:129], v[134:137], v[178:181], v[126:129]
	v_mfma_f32_16x16x32_bf16 v[126:129], v[138:141], v[182:185], v[126:129]
	v_mfma_f32_16x16x32_bf16 v[122:125], v[142:145], v[178:181], v[122:125]
	v_mfma_f32_16x16x32_bf16 v[122:125], v[146:149], v[182:185], v[122:125]
	v_mfma_f32_16x16x32_bf16 v[110:113], v[134:137], v[186:189], v[110:113]
	v_mfma_f32_16x16x32_bf16 v[110:113], v[138:141], v[190:193], v[110:113]
	v_mfma_f32_16x16x32_bf16 v[106:109], v[142:145], v[186:189], v[106:109]
	v_mfma_f32_16x16x32_bf16 v[106:109], v[146:149], v[190:193], v[106:109]
	v_mfma_f32_16x16x32_bf16 v[94:97], v[134:137], v[204:207], v[94:97]
	v_mfma_f32_16x16x32_bf16 v[94:97], v[138:141], v[208:211], v[94:97]
	v_mfma_f32_16x16x32_bf16 v[90:93], v[142:145], v[204:207], v[90:93]
	v_mfma_f32_16x16x32_bf16 v[90:93], v[146:149], v[208:211], v[90:93]
	v_mfma_f32_16x16x32_bf16 v[78:81], v[134:137], v[212:215], v[78:81]
	v_mfma_f32_16x16x32_bf16 v[78:81], v[138:141], v[216:219], v[78:81]
	v_mfma_f32_16x16x32_bf16 v[74:77], v[142:145], v[212:215], v[74:77]
	v_mfma_f32_16x16x32_bf16 v[74:77], v[146:149], v[216:219], v[74:77]
	s_setprio 0
	s_setprio 1
	v_mfma_f32_16x16x32_bf16 v[118:121], v[150:153], v[178:181], v[118:121]
	v_mfma_f32_16x16x32_bf16 v[118:121], v[154:157], v[182:185], v[118:121]
	v_mfma_f32_16x16x32_bf16 v[114:117], v[158:161], v[178:181], v[114:117]
	v_mfma_f32_16x16x32_bf16 v[114:117], v[174:177], v[182:185], v[114:117]
	v_mfma_f32_16x16x32_bf16 v[102:105], v[150:153], v[186:189], v[102:105]
	v_mfma_f32_16x16x32_bf16 v[102:105], v[154:157], v[190:193], v[102:105]
	v_mfma_f32_16x16x32_bf16 v[98:101], v[158:161], v[186:189], v[98:101]
	v_mfma_f32_16x16x32_bf16 v[98:101], v[174:177], v[190:193], v[98:101]
	v_mfma_f32_16x16x32_bf16 v[86:89], v[150:153], v[204:207], v[86:89]
	v_mfma_f32_16x16x32_bf16 v[86:89], v[154:157], v[208:211], v[86:89]
	v_mfma_f32_16x16x32_bf16 v[82:85], v[158:161], v[204:207], v[82:85]
	v_mfma_f32_16x16x32_bf16 v[82:85], v[174:177], v[208:211], v[82:85]
	v_mfma_f32_16x16x32_bf16 v[70:73], v[150:153], v[212:215], v[70:73]
	v_mfma_f32_16x16x32_bf16 v[70:73], v[154:157], v[216:219], v[70:73]
	v_mfma_f32_16x16x32_bf16 v[66:69], v[158:161], v[212:215], v[66:69]
	v_mfma_f32_16x16x32_bf16 v[66:69], v[174:177], v[216:219], v[66:69]
	s_setprio 0
	s_barrier
	s_add_i32 s0, s0, s54
	v_lshl_add_u64 v[220:221], s[70:71], 0, v[164:165]
	s_mov_b32 m0, s0
	ds_read_b128 v[178:181], v222 offset:16384
	ds_read_b128 v[182:185], v222 offset:17408
	ds_read_b128 v[186:189], v222 offset:18432
	ds_read_b128 v[190:193], v222 offset:19456
	ds_read_b128 v[204:207], v222 offset:20480
	ds_read_b128 v[208:211], v222 offset:21504
	ds_read_b128 v[212:215], v222 offset:22528
	ds_read_b128 v[216:219], v222 offset:23552
	global_load_lds_dwordx4 v[220:221], off
	s_add_i32 m0, s0, 0x2000
	s_add_u32 s44, s70, 0x80000
	v_lshl_add_u64 v[224:225], s[70:71], 0, v[162:163]
	s_addc_u32 s45, s71, 0
	s_add_i32 s0, s1, s54
	global_load_lds_dwordx4 v[224:225], off
	v_lshl_add_u64 v[226:227], s[44:45], 0, v[164:165]
	s_mov_b32 m0, s0
	v_lshl_add_u64 v[228:229], vcc, 0, v[162:163]
	global_load_lds_dwordx4 v[226:227], off
	v_lshl_add_u64 v[226:227], s[44:45], 0, v[162:163]
	s_add_i32 m0, s0, 0x2000
	s_nop 0
	global_load_lds_dwordx4 v[226:227], off
	v_lshl_add_u64 v[226:227], vcc, 0, v[164:165]
	s_mov_b32 m0, s67
	s_nop 0
	global_load_lds_dwordx4 v[226:227], off
	s_mov_b32 m0, s68
	s_nop 0
	global_load_lds_dwordx4 v[228:229], off
	s_waitcnt vmcnt(8)
	s_waitcnt lgkmcnt(0)
	s_barrier
	s_setprio 1
	s_waitcnt lgkmcnt(0)
	v_mfma_f32_16x16x32_bf16 v[62:65], v[134:137], v[178:181], v[62:65]
	v_mfma_f32_16x16x32_bf16 v[62:65], v[138:141], v[182:185], v[62:65]
	v_mfma_f32_16x16x32_bf16 v[58:61], v[142:145], v[178:181], v[58:61]
	v_mfma_f32_16x16x32_bf16 v[58:61], v[146:149], v[182:185], v[58:61]
	v_mfma_f32_16x16x32_bf16 v[46:49], v[134:137], v[186:189], v[46:49]
	v_mfma_f32_16x16x32_bf16 v[46:49], v[138:141], v[190:193], v[46:49]
	v_mfma_f32_16x16x32_bf16 v[42:45], v[142:145], v[186:189], v[42:45]
	v_mfma_f32_16x16x32_bf16 v[42:45], v[146:149], v[190:193], v[42:45]
	v_mfma_f32_16x16x32_bf16 v[30:33], v[134:137], v[204:207], v[30:33]
	v_mfma_f32_16x16x32_bf16 v[30:33], v[138:141], v[208:211], v[30:33]
	v_mfma_f32_16x16x32_bf16 v[26:29], v[142:145], v[204:207], v[26:29]
	v_mfma_f32_16x16x32_bf16 v[26:29], v[146:149], v[208:211], v[26:29]
	v_mfma_f32_16x16x32_bf16 v[14:17], v[134:137], v[212:215], v[14:17]
	v_mfma_f32_16x16x32_bf16 v[14:17], v[138:141], v[216:219], v[14:17]
	v_mfma_f32_16x16x32_bf16 v[10:13], v[142:145], v[212:215], v[10:13]
	v_mfma_f32_16x16x32_bf16 v[10:13], v[146:149], v[216:219], v[10:13]
	s_setprio 0
	s_setprio 1
	v_mfma_f32_16x16x32_bf16 v[54:57], v[150:153], v[178:181], v[54:57]
	v_mfma_f32_16x16x32_bf16 v[54:57], v[154:157], v[182:185], v[54:57]
	v_mfma_f32_16x16x32_bf16 v[50:53], v[158:161], v[178:181], v[50:53]
	v_mfma_f32_16x16x32_bf16 v[50:53], v[174:177], v[182:185], v[50:53]
	v_mfma_f32_16x16x32_bf16 v[38:41], v[150:153], v[186:189], v[38:41]
	v_mfma_f32_16x16x32_bf16 v[38:41], v[154:157], v[190:193], v[38:41]
	v_mfma_f32_16x16x32_bf16 v[34:37], v[158:161], v[186:189], v[34:37]
	v_mfma_f32_16x16x32_bf16 v[34:37], v[174:177], v[190:193], v[34:37]
	v_mfma_f32_16x16x32_bf16 v[22:25], v[150:153], v[204:207], v[22:25]
	v_mfma_f32_16x16x32_bf16 v[22:25], v[154:157], v[208:211], v[22:25]
	v_mfma_f32_16x16x32_bf16 v[18:21], v[158:161], v[204:207], v[18:21]
	v_mfma_f32_16x16x32_bf16 v[18:21], v[174:177], v[208:211], v[18:21]
	v_mfma_f32_16x16x32_bf16 v[6:9], v[150:153], v[212:215], v[6:9]
	v_mfma_f32_16x16x32_bf16 v[6:9], v[154:157], v[216:219], v[6:9]
	v_mfma_f32_16x16x32_bf16 v[2:5], v[158:161], v[212:215], v[2:5]
	v_mfma_f32_16x16x32_bf16 v[2:5], v[174:177], v[216:219], v[2:5]
	s_setprio 0
	s_barrier
	s_add_i32 s0, 0, 0x18000
	s_add_i32 s1, 0, 0x1c000
	v_add_u32_e32 v146, s0, v1
	v_add_u32_e32 v174, s1, v1
	ds_read_b128 v[134:137], v146
	ds_read_b128 v[138:141], v146 offset:1024
	ds_read_b128 v[142:145], v146 offset:2048
	ds_read_b128 v[146:149], v146 offset:3072
	ds_read_b128 v[150:153], v174
	ds_read_b128 v[154:157], v174 offset:1024
	ds_read_b128 v[158:161], v174 offset:2048
	ds_read_b128 v[174:177], v174 offset:3072
	s_add_u32 s44, vcc_lo, 0x80000
	s_addc_u32 s45, vcc_hi, 0
	s_mov_b32 m0, s8
	v_lshl_add_u64 v[230:231], s[44:45], 0, v[164:165]
	ds_read_b128 v[178:181], v222 offset:32768
	ds_read_b128 v[182:185], v222 offset:33792
	ds_read_b128 v[186:189], v222 offset:34816
	ds_read_b128 v[190:193], v222 offset:35840
	ds_read_b128 v[204:207], v222 offset:36864
	ds_read_b128 v[208:211], v222 offset:37888
	ds_read_b128 v[212:215], v222 offset:38912
	ds_read_b128 v[216:219], v222 offset:39936
	global_load_lds_dwordx4 v[230:231], off
	v_lshl_add_u64 v[230:231], s[44:45], 0, v[162:163]
	s_mov_b32 m0, s9
	s_nop 0
	global_load_lds_dwordx4 v[230:231], off
	s_waitcnt vmcnt(8)
	s_waitcnt lgkmcnt(0)
	s_barrier
	s_setprio 1
	s_waitcnt lgkmcnt(0)
	v_mfma_f32_16x16x32_bf16 v[126:129], v[134:137], v[178:181], v[126:129]
	v_mfma_f32_16x16x32_bf16 v[126:129], v[138:141], v[182:185], v[126:129]
	v_mfma_f32_16x16x32_bf16 v[122:125], v[142:145], v[178:181], v[122:125]
	v_mfma_f32_16x16x32_bf16 v[122:125], v[146:149], v[182:185], v[122:125]
	v_mfma_f32_16x16x32_bf16 v[110:113], v[134:137], v[186:189], v[110:113]
	v_mfma_f32_16x16x32_bf16 v[110:113], v[138:141], v[190:193], v[110:113]
	v_mfma_f32_16x16x32_bf16 v[106:109], v[142:145], v[186:189], v[106:109]
	v_mfma_f32_16x16x32_bf16 v[106:109], v[146:149], v[190:193], v[106:109]
	v_mfma_f32_16x16x32_bf16 v[94:97], v[134:137], v[204:207], v[94:97]
	v_mfma_f32_16x16x32_bf16 v[94:97], v[138:141], v[208:211], v[94:97]
	v_mfma_f32_16x16x32_bf16 v[90:93], v[142:145], v[204:207], v[90:93]
	v_mfma_f32_16x16x32_bf16 v[90:93], v[146:149], v[208:211], v[90:93]
	v_mfma_f32_16x16x32_bf16 v[78:81], v[134:137], v[212:215], v[78:81]
	v_mfma_f32_16x16x32_bf16 v[78:81], v[138:141], v[216:219], v[78:81]
	v_mfma_f32_16x16x32_bf16 v[74:77], v[142:145], v[212:215], v[74:77]
	v_mfma_f32_16x16x32_bf16 v[74:77], v[146:149], v[216:219], v[74:77]
	s_setprio 0
	s_setprio 1
	v_mfma_f32_16x16x32_bf16 v[118:121], v[150:153], v[178:181], v[118:121]
	v_mfma_f32_16x16x32_bf16 v[118:121], v[154:157], v[182:185], v[118:121]
	v_mfma_f32_16x16x32_bf16 v[114:117], v[158:161], v[178:181], v[114:117]
	v_mfma_f32_16x16x32_bf16 v[114:117], v[174:177], v[182:185], v[114:117]
	v_mfma_f32_16x16x32_bf16 v[102:105], v[150:153], v[186:189], v[102:105]
	v_mfma_f32_16x16x32_bf16 v[102:105], v[154:157], v[190:193], v[102:105]
	v_mfma_f32_16x16x32_bf16 v[98:101], v[158:161], v[186:189], v[98:101]
	v_mfma_f32_16x16x32_bf16 v[98:101], v[174:177], v[190:193], v[98:101]
	v_mfma_f32_16x16x32_bf16 v[86:89], v[150:153], v[204:207], v[86:89]
	v_mfma_f32_16x16x32_bf16 v[86:89], v[154:157], v[208:211], v[86:89]
	v_mfma_f32_16x16x32_bf16 v[82:85], v[158:161], v[204:207], v[82:85]
	v_mfma_f32_16x16x32_bf16 v[82:85], v[174:177], v[208:211], v[82:85]
	v_mfma_f32_16x16x32_bf16 v[70:73], v[150:153], v[212:215], v[70:73]
	v_mfma_f32_16x16x32_bf16 v[70:73], v[154:157], v[216:219], v[70:73]
	v_mfma_f32_16x16x32_bf16 v[66:69], v[158:161], v[212:215], v[66:69]
	v_mfma_f32_16x16x32_bf16 v[66:69], v[174:177], v[216:219], v[66:69]
	s_setprio 0
	s_barrier
	s_add_i32 s0, s0, s54
	v_lshl_add_u64 v[220:221], v[220:221], 0, s[82:83]
	s_mov_b32 m0, s0
	ds_read_b128 v[178:181], v222 offset:49152
	ds_read_b128 v[182:185], v222 offset:50176
	ds_read_b128 v[186:189], v222 offset:51200
	ds_read_b128 v[190:193], v222 offset:52224
	ds_read_b128 v[204:207], v222 offset:53248
	ds_read_b128 v[208:211], v222 offset:54272
	ds_read_b128 v[212:215], v222 offset:55296
	ds_read_b128 v[216:219], v222 offset:56320
	global_load_lds_dwordx4 v[220:221], off
	s_add_i32 m0, s0, 0x2000
	s_add_u32 s44, s70, 0x80080
	v_lshl_add_u64 v[220:221], v[224:225], 0, s[82:83]
	s_addc_u32 s45, s71, 0
	s_add_i32 s0, s1, s54
	global_load_lds_dwordx4 v[220:221], off
	v_lshl_add_u64 v[220:221], s[44:45], 0, v[164:165]
	s_mov_b32 m0, s0
	s_nop 0
	global_load_lds_dwordx4 v[220:221], off
	v_lshl_add_u64 v[220:221], s[44:45], 0, v[162:163]
	s_add_i32 m0, s0, 0x2000
	s_nop 0
	global_load_lds_dwordx4 v[220:221], off
	v_lshl_add_u64 v[220:221], v[226:227], 0, s[82:83]
	s_mov_b32 m0, s27
	s_nop 0
	global_load_lds_dwordx4 v[220:221], off
	v_lshl_add_u64 v[220:221], v[228:229], 0, s[82:83]
	s_mov_b32 m0, s26
	s_nop 0
	global_load_lds_dwordx4 v[220:221], off
	s_waitcnt vmcnt(8)
	s_waitcnt lgkmcnt(0)
	s_barrier
	s_setprio 1
	s_waitcnt lgkmcnt(0)
	v_mfma_f32_16x16x32_bf16 v[62:65], v[134:137], v[178:181], v[62:65]
	v_mfma_f32_16x16x32_bf16 v[62:65], v[138:141], v[182:185], v[62:65]
	v_mfma_f32_16x16x32_bf16 v[58:61], v[142:145], v[178:181], v[58:61]
	v_mfma_f32_16x16x32_bf16 v[58:61], v[146:149], v[182:185], v[58:61]
	v_mfma_f32_16x16x32_bf16 v[46:49], v[134:137], v[186:189], v[46:49]
	v_mfma_f32_16x16x32_bf16 v[46:49], v[138:141], v[190:193], v[46:49]
	v_mfma_f32_16x16x32_bf16 v[42:45], v[142:145], v[186:189], v[42:45]
	v_mfma_f32_16x16x32_bf16 v[42:45], v[146:149], v[190:193], v[42:45]
	v_mfma_f32_16x16x32_bf16 v[30:33], v[134:137], v[204:207], v[30:33]
	v_mfma_f32_16x16x32_bf16 v[30:33], v[138:141], v[208:211], v[30:33]
	v_mfma_f32_16x16x32_bf16 v[26:29], v[142:145], v[204:207], v[26:29]
	v_mfma_f32_16x16x32_bf16 v[26:29], v[146:149], v[208:211], v[26:29]
	v_mfma_f32_16x16x32_bf16 v[14:17], v[134:137], v[212:215], v[14:17]
	v_mfma_f32_16x16x32_bf16 v[14:17], v[138:141], v[216:219], v[14:17]
	v_mfma_f32_16x16x32_bf16 v[10:13], v[142:145], v[212:215], v[10:13]
	v_mfma_f32_16x16x32_bf16 v[10:13], v[146:149], v[216:219], v[10:13]
	s_setprio 0
	s_setprio 1
	v_mfma_f32_16x16x32_bf16 v[54:57], v[150:153], v[178:181], v[54:57]
	v_mfma_f32_16x16x32_bf16 v[54:57], v[154:157], v[182:185], v[54:57]
	v_mfma_f32_16x16x32_bf16 v[50:53], v[158:161], v[178:181], v[50:53]
	v_mfma_f32_16x16x32_bf16 v[50:53], v[174:177], v[182:185], v[50:53]
	v_mfma_f32_16x16x32_bf16 v[38:41], v[150:153], v[186:189], v[38:41]
	v_mfma_f32_16x16x32_bf16 v[38:41], v[154:157], v[190:193], v[38:41]
	v_mfma_f32_16x16x32_bf16 v[34:37], v[158:161], v[186:189], v[34:37]
	v_mfma_f32_16x16x32_bf16 v[34:37], v[174:177], v[190:193], v[34:37]
	v_mfma_f32_16x16x32_bf16 v[22:25], v[150:153], v[204:207], v[22:25]
	v_mfma_f32_16x16x32_bf16 v[22:25], v[154:157], v[208:211], v[22:25]
	v_mfma_f32_16x16x32_bf16 v[18:21], v[158:161], v[204:207], v[18:21]
	v_mfma_f32_16x16x32_bf16 v[18:21], v[174:177], v[208:211], v[18:21]
	v_mfma_f32_16x16x32_bf16 v[6:9], v[150:153], v[212:215], v[6:9]
	v_mfma_f32_16x16x32_bf16 v[6:9], v[154:157], v[216:219], v[6:9]
	v_mfma_f32_16x16x32_bf16 v[2:5], v[158:161], v[212:215], v[2:5]
	v_mfma_f32_16x16x32_bf16 v[2:5], v[174:177], v[216:219], v[2:5]
	s_setprio 0
	s_barrier
	s_add_i32 s43, s43, 2
	s_add_u32 s76, s76, 0x100
	s_addc_u32 s77, s77, 0
	s_add_u32 s7, s7, 0x100
	s_addc_u32 s41, s41, 0
	s_cmp_gt_u32 s43, 29
	s_cbranch_scc1 .LBB0_288

.LBB0_509:
	s_add_u32 s90, s76, 0x100
	s_addc_u32 s91, s77, 0
	s_and_b64 s[0:1], s[70:71], exec
	s_cselect_b32 vcc_hi, s22, s91
	s_cselect_b32 vcc_lo, s23, s90
	s_cselect_b32 s71, s41, s53
	s_cselect_b32 s70, s44, s51
	s_add_i32 s0, 0, 0x10000
	s_add_i32 s18, 0, 0x14000
	v_add_u32_e32 v114, s0, v1
	v_add_u32_e32 v154, s18, v1
	ds_read_b128 v[78:81], v114
	ds_read_b128 v[90:93], v114 offset:1024
	ds_read_b128 v[102:105], v114 offset:2048
	ds_read_b128 v[114:117], v114 offset:3072
	ds_read_b128 v[126:129], v154
	ds_read_b128 v[134:137], v154 offset:1024
	ds_read_b128 v[142:145], v154 offset:2048
	ds_read_b128 v[154:157], v154 offset:3072
	v_lshl_add_u64 v[218:219], s[76:77], 0, v[210:211]
	s_add_i32 m0, s29, 0xc000
	ds_read_b128 v[158:161], v237
	ds_read_b128 v[162:165], v237 offset:1024
	ds_read_b128 v[166:169], v237 offset:2048
	ds_read_b128 v[178:181], v237 offset:3072
	ds_read_b128 v[182:185], v237 offset:4096
	ds_read_b128 v[186:189], v237 offset:5120
	ds_read_b128 v[190:193], v237 offset:6144
	ds_read_b128 v[214:217], v237 offset:7168
	global_load_lds_dwordx4 v[218:219], off
	v_lshl_add_u64 v[218:219], s[76:77], 0, v[212:213]
	s_add_i32 m0, s29, 0xe000
	s_nop 0
	global_load_lds_dwordx4 v[218:219], off
	s_waitcnt vmcnt(8)
	s_waitcnt lgkmcnt(0)
	s_barrier
	s_setprio 1
	s_waitcnt lgkmcnt(0)
	v_mfma_f32_16x16x32_bf16 v[174:177], v[78:81], v[158:161], v[174:177]
	v_mfma_f32_16x16x32_bf16 v[174:177], v[90:93], v[162:165], v[174:177]
	v_mfma_f32_16x16x32_bf16 v[170:173], v[102:105], v[158:161], v[170:173]
	v_mfma_f32_16x16x32_bf16 v[170:173], v[114:117], v[162:165], v[170:173]
	v_mfma_f32_16x16x32_bf16 v[138:141], v[78:81], v[166:169], v[138:141]
	v_mfma_f32_16x16x32_bf16 v[138:141], v[90:93], v[178:181], v[138:141]
	v_mfma_f32_16x16x32_bf16 v[130:133], v[102:105], v[166:169], v[130:133]
	v_mfma_f32_16x16x32_bf16 v[130:133], v[114:117], v[178:181], v[130:133]
	v_mfma_f32_16x16x32_bf16 v[110:113], v[78:81], v[182:185], v[110:113]
	v_mfma_f32_16x16x32_bf16 v[110:113], v[90:93], v[186:189], v[110:113]
	v_mfma_f32_16x16x32_bf16 v[106:109], v[102:105], v[182:185], v[106:109]
	v_mfma_f32_16x16x32_bf16 v[106:109], v[114:117], v[186:189], v[106:109]
	v_mfma_f32_16x16x32_bf16 v[86:89], v[78:81], v[190:193], v[86:89]
	v_mfma_f32_16x16x32_bf16 v[86:89], v[90:93], v[214:217], v[86:89]
	v_mfma_f32_16x16x32_bf16 v[82:85], v[102:105], v[190:193], v[82:85]
	v_mfma_f32_16x16x32_bf16 v[82:85], v[114:117], v[214:217], v[82:85]
	s_setprio 0
	s_setprio 1
	v_mfma_f32_16x16x32_bf16 v[150:153], v[126:129], v[158:161], v[150:153]
	v_mfma_f32_16x16x32_bf16 v[150:153], v[134:137], v[162:165], v[150:153]
	v_mfma_f32_16x16x32_bf16 v[146:149], v[142:145], v[158:161], v[146:149]
	v_mfma_f32_16x16x32_bf16 v[146:149], v[154:157], v[162:165], v[146:149]
	v_mfma_f32_16x16x32_bf16 v[122:125], v[126:129], v[166:169], v[122:125]
	v_mfma_f32_16x16x32_bf16 v[122:125], v[134:137], v[178:181], v[122:125]
	v_mfma_f32_16x16x32_bf16 v[118:121], v[142:145], v[166:169], v[118:121]
	v_mfma_f32_16x16x32_bf16 v[118:121], v[154:157], v[178:181], v[118:121]
	v_mfma_f32_16x16x32_bf16 v[98:101], v[126:129], v[182:185], v[98:101]
	v_mfma_f32_16x16x32_bf16 v[98:101], v[134:137], v[186:189], v[98:101]
	v_mfma_f32_16x16x32_bf16 v[94:97], v[142:145], v[182:185], v[94:97]
	v_mfma_f32_16x16x32_bf16 v[94:97], v[154:157], v[186:189], v[94:97]
	v_mfma_f32_16x16x32_bf16 v[74:77], v[126:129], v[190:193], v[74:77]
	v_mfma_f32_16x16x32_bf16 v[74:77], v[134:137], v[214:217], v[74:77]
	v_mfma_f32_16x16x32_bf16 v[66:69], v[142:145], v[190:193], v[66:69]
	v_mfma_f32_16x16x32_bf16 v[66:69], v[154:157], v[214:217], v[66:69]
	s_setprio 0
	s_barrier
	s_add_i32 s0, s0, s28
	v_lshl_add_u64 v[218:219], s[70:71], 0, v[194:195]
	s_mov_b32 m0, s0
	ds_read_b128 v[158:161], v237 offset:16384
	ds_read_b128 v[162:165], v237 offset:17408
	ds_read_b128 v[166:169], v237 offset:18432
	ds_read_b128 v[178:181], v237 offset:19456
	ds_read_b128 v[182:185], v237 offset:20480
	ds_read_b128 v[186:189], v237 offset:21504
	ds_read_b128 v[190:193], v237 offset:22528
	ds_read_b128 v[214:217], v237 offset:23552
	global_load_lds_dwordx4 v[218:219], off
	s_add_i32 m0, s0, 0x2000
	s_add_u32 s0, s70, 0x80000
	v_lshl_add_u64 v[220:221], s[70:71], 0, v[204:205]
	s_addc_u32 s1, s71, 0
	s_add_i32 s18, s18, s28
	global_load_lds_dwordx4 v[220:221], off
	v_lshl_add_u64 v[222:223], s[0:1], 0, v[194:195]
	s_mov_b32 m0, s18
	v_lshl_add_u64 v[224:225], vcc, 0, v[204:205]
	global_load_lds_dwordx4 v[222:223], off
	v_lshl_add_u64 v[222:223], s[0:1], 0, v[204:205]
	s_add_i32 m0, s18, 0x2000
	s_nop 0
	global_load_lds_dwordx4 v[222:223], off
	v_lshl_add_u64 v[222:223], vcc, 0, v[194:195]
	s_mov_b32 m0, s29
	s_nop 0
	global_load_lds_dwordx4 v[222:223], off
	s_mov_b32 m0, s31
	s_nop 0
	global_load_lds_dwordx4 v[224:225], off
	s_waitcnt vmcnt(8)
	s_waitcnt lgkmcnt(0)
	s_barrier
	s_setprio 1
	s_waitcnt lgkmcnt(0)
	v_mfma_f32_16x16x32_bf16 v[62:65], v[78:81], v[158:161], v[62:65]
	v_mfma_f32_16x16x32_bf16 v[62:65], v[90:93], v[162:165], v[62:65]
	v_mfma_f32_16x16x32_bf16 v[58:61], v[102:105], v[158:161], v[58:61]
	v_mfma_f32_16x16x32_bf16 v[58:61], v[114:117], v[162:165], v[58:61]
	v_mfma_f32_16x16x32_bf16 v[46:49], v[78:81], v[166:169], v[46:49]
	v_mfma_f32_16x16x32_bf16 v[46:49], v[90:93], v[178:181], v[46:49]
	v_mfma_f32_16x16x32_bf16 v[42:45], v[102:105], v[166:169], v[42:45]
	v_mfma_f32_16x16x32_bf16 v[42:45], v[114:117], v[178:181], v[42:45]
	v_mfma_f32_16x16x32_bf16 v[30:33], v[78:81], v[182:185], v[30:33]
	v_mfma_f32_16x16x32_bf16 v[30:33], v[90:93], v[186:189], v[30:33]
	v_mfma_f32_16x16x32_bf16 v[26:29], v[102:105], v[182:185], v[26:29]
	v_mfma_f32_16x16x32_bf16 v[26:29], v[114:117], v[186:189], v[26:29]
	v_mfma_f32_16x16x32_bf16 v[14:17], v[78:81], v[190:193], v[14:17]
	v_mfma_f32_16x16x32_bf16 v[14:17], v[90:93], v[214:217], v[14:17]
	v_mfma_f32_16x16x32_bf16 v[10:13], v[102:105], v[190:193], v[10:13]
	v_mfma_f32_16x16x32_bf16 v[10:13], v[114:117], v[214:217], v[10:13]
	s_setprio 0
	s_setprio 1
	v_mfma_f32_16x16x32_bf16 v[54:57], v[126:129], v[158:161], v[54:57]
	v_mfma_f32_16x16x32_bf16 v[54:57], v[134:137], v[162:165], v[54:57]
	v_mfma_f32_16x16x32_bf16 v[50:53], v[142:145], v[158:161], v[50:53]
	v_mfma_f32_16x16x32_bf16 v[50:53], v[154:157], v[162:165], v[50:53]
	v_mfma_f32_16x16x32_bf16 v[38:41], v[126:129], v[166:169], v[38:41]
	v_mfma_f32_16x16x32_bf16 v[38:41], v[134:137], v[178:181], v[38:41]
	v_mfma_f32_16x16x32_bf16 v[34:37], v[142:145], v[166:169], v[34:37]
	v_mfma_f32_16x16x32_bf16 v[34:37], v[154:157], v[178:181], v[34:37]
	v_mfma_f32_16x16x32_bf16 v[22:25], v[126:129], v[182:185], v[22:25]
	v_mfma_f32_16x16x32_bf16 v[22:25], v[134:137], v[186:189], v[22:25]
	v_mfma_f32_16x16x32_bf16 v[18:21], v[142:145], v[182:185], v[18:21]
	v_mfma_f32_16x16x32_bf16 v[18:21], v[154:157], v[186:189], v[18:21]
	v_mfma_f32_16x16x32_bf16 v[6:9], v[126:129], v[190:193], v[6:9]
	v_mfma_f32_16x16x32_bf16 v[6:9], v[134:137], v[214:217], v[6:9]
	v_mfma_f32_16x16x32_bf16 v[2:5], v[142:145], v[190:193], v[2:5]
	v_mfma_f32_16x16x32_bf16 v[2:5], v[154:157], v[214:217], v[2:5]
	s_setprio 0
	s_barrier
	s_add_i32 s18, 0, 0x18000
	s_add_i32 s19, 0, 0x1c000
	v_add_u32_e32 v114, s18, v1
	v_add_u32_e32 v154, s19, v1
	ds_read_b128 v[78:81], v114
	ds_read_b128 v[90:93], v114 offset:1024
	ds_read_b128 v[102:105], v114 offset:2048
	ds_read_b128 v[114:117], v114 offset:3072
	ds_read_b128 v[126:129], v154
	ds_read_b128 v[134:137], v154 offset:1024
	ds_read_b128 v[142:145], v154 offset:2048
	ds_read_b128 v[154:157], v154 offset:3072
	s_add_u32 s0, vcc_lo, 0x80000
	s_addc_u32 s1, vcc_hi, 0
	s_mov_b32 m0, s33
	v_lshl_add_u64 v[226:227], s[0:1], 0, v[194:195]
	ds_read_b128 v[158:161], v237 offset:32768
	ds_read_b128 v[162:165], v237 offset:33792
	ds_read_b128 v[166:169], v237 offset:34816
	ds_read_b128 v[178:181], v237 offset:35840
	ds_read_b128 v[182:185], v237 offset:36864
	ds_read_b128 v[186:189], v237 offset:37888
	ds_read_b128 v[190:193], v237 offset:38912
	ds_read_b128 v[214:217], v237 offset:39936
	global_load_lds_dwordx4 v[226:227], off
	v_lshl_add_u64 v[226:227], s[0:1], 0, v[204:205]
	s_mov_b32 m0, s43
	s_nop 0
	global_load_lds_dwordx4 v[226:227], off
	s_waitcnt vmcnt(8)
	s_waitcnt lgkmcnt(0)
	s_barrier
	s_setprio 1
	s_waitcnt lgkmcnt(0)
	v_mfma_f32_16x16x32_bf16 v[174:177], v[78:81], v[158:161], v[174:177]
	v_mfma_f32_16x16x32_bf16 v[174:177], v[90:93], v[162:165], v[174:177]
	v_mfma_f32_16x16x32_bf16 v[170:173], v[102:105], v[158:161], v[170:173]
	v_mfma_f32_16x16x32_bf16 v[170:173], v[114:117], v[162:165], v[170:173]
	v_mfma_f32_16x16x32_bf16 v[138:141], v[78:81], v[166:169], v[138:141]
	v_mfma_f32_16x16x32_bf16 v[138:141], v[90:93], v[178:181], v[138:141]
	v_mfma_f32_16x16x32_bf16 v[130:133], v[102:105], v[166:169], v[130:133]
	v_mfma_f32_16x16x32_bf16 v[130:133], v[114:117], v[178:181], v[130:133]
	v_mfma_f32_16x16x32_bf16 v[110:113], v[78:81], v[182:185], v[110:113]
	v_mfma_f32_16x16x32_bf16 v[110:113], v[90:93], v[186:189], v[110:113]
	v_mfma_f32_16x16x32_bf16 v[106:109], v[102:105], v[182:185], v[106:109]
	v_mfma_f32_16x16x32_bf16 v[106:109], v[114:117], v[186:189], v[106:109]
	v_mfma_f32_16x16x32_bf16 v[86:89], v[78:81], v[190:193], v[86:89]
	v_mfma_f32_16x16x32_bf16 v[86:89], v[90:93], v[214:217], v[86:89]
	v_mfma_f32_16x16x32_bf16 v[82:85], v[102:105], v[190:193], v[82:85]
	v_mfma_f32_16x16x32_bf16 v[82:85], v[114:117], v[214:217], v[82:85]
	s_setprio 0
	s_setprio 1
	v_mfma_f32_16x16x32_bf16 v[150:153], v[126:129], v[158:161], v[150:153]
	v_mfma_f32_16x16x32_bf16 v[150:153], v[134:137], v[162:165], v[150:153]
	v_mfma_f32_16x16x32_bf16 v[146:149], v[142:145], v[158:161], v[146:149]
	v_mfma_f32_16x16x32_bf16 v[146:149], v[154:157], v[162:165], v[146:149]
	v_mfma_f32_16x16x32_bf16 v[122:125], v[126:129], v[166:169], v[122:125]
	v_mfma_f32_16x16x32_bf16 v[122:125], v[134:137], v[178:181], v[122:125]
	v_mfma_f32_16x16x32_bf16 v[118:121], v[142:145], v[166:169], v[118:121]
	v_mfma_f32_16x16x32_bf16 v[118:121], v[154:157], v[178:181], v[118:121]
	v_mfma_f32_16x16x32_bf16 v[98:101], v[126:129], v[182:185], v[98:101]
	v_mfma_f32_16x16x32_bf16 v[98:101], v[134:137], v[186:189], v[98:101]
	v_mfma_f32_16x16x32_bf16 v[94:97], v[142:145], v[182:185], v[94:97]
	v_mfma_f32_16x16x32_bf16 v[94:97], v[154:157], v[186:189], v[94:97]
	v_mfma_f32_16x16x32_bf16 v[74:77], v[126:129], v[190:193], v[74:77]
	v_mfma_f32_16x16x32_bf16 v[74:77], v[134:137], v[214:217], v[74:77]
	v_mfma_f32_16x16x32_bf16 v[66:69], v[142:145], v[190:193], v[66:69]
	v_mfma_f32_16x16x32_bf16 v[66:69], v[154:157], v[214:217], v[66:69]
	s_setprio 0
	s_barrier
	s_add_i32 s0, s18, s28
	v_lshl_add_u64 v[218:219], v[218:219], 0, s[82:83]
	s_mov_b32 m0, s0
	ds_read_b128 v[158:161], v237 offset:49152
	ds_read_b128 v[162:165], v237 offset:50176
	ds_read_b128 v[166:169], v237 offset:51200
	ds_read_b128 v[178:181], v237 offset:52224
	ds_read_b128 v[182:185], v237 offset:53248
	ds_read_b128 v[186:189], v237 offset:54272
	ds_read_b128 v[190:193], v237 offset:55296
	ds_read_b128 v[214:217], v237 offset:56320
	global_load_lds_dwordx4 v[218:219], off
	s_add_i32 m0, s0, 0x2000
	s_add_u32 s0, s70, 0x80080
	v_lshl_add_u64 v[218:219], v[220:221], 0, s[82:83]
	s_addc_u32 s1, s71, 0
	s_add_i32 s18, s19, s28
	global_load_lds_dwordx4 v[218:219], off
	v_lshl_add_u64 v[218:219], s[0:1], 0, v[194:195]
	s_mov_b32 m0, s18
	s_nop 0
	global_load_lds_dwordx4 v[218:219], off
	v_lshl_add_u64 v[218:219], s[0:1], 0, v[204:205]
	s_add_i32 m0, s18, 0x2000
	s_nop 0
	global_load_lds_dwordx4 v[218:219], off
	v_lshl_add_u64 v[218:219], v[222:223], 0, s[82:83]
	s_mov_b32 m0, s68
	s_nop 0
	global_load_lds_dwordx4 v[218:219], off
	v_lshl_add_u64 v[218:219], v[224:225], 0, s[82:83]
	s_mov_b32 m0, s79
	s_nop 0
	global_load_lds_dwordx4 v[218:219], off
	s_waitcnt vmcnt(8)
	s_waitcnt lgkmcnt(0)
	s_barrier
	s_setprio 1
	s_waitcnt lgkmcnt(0)
	v_mfma_f32_16x16x32_bf16 v[62:65], v[78:81], v[158:161], v[62:65]
	v_mfma_f32_16x16x32_bf16 v[62:65], v[90:93], v[162:165], v[62:65]
	v_mfma_f32_16x16x32_bf16 v[58:61], v[102:105], v[158:161], v[58:61]
	v_mfma_f32_16x16x32_bf16 v[58:61], v[114:117], v[162:165], v[58:61]
	v_mfma_f32_16x16x32_bf16 v[46:49], v[78:81], v[166:169], v[46:49]
	v_mfma_f32_16x16x32_bf16 v[46:49], v[90:93], v[178:181], v[46:49]
	v_mfma_f32_16x16x32_bf16 v[42:45], v[102:105], v[166:169], v[42:45]
	v_mfma_f32_16x16x32_bf16 v[42:45], v[114:117], v[178:181], v[42:45]
	v_mfma_f32_16x16x32_bf16 v[30:33], v[78:81], v[182:185], v[30:33]
	v_mfma_f32_16x16x32_bf16 v[30:33], v[90:93], v[186:189], v[30:33]
	v_mfma_f32_16x16x32_bf16 v[26:29], v[102:105], v[182:185], v[26:29]
	v_mfma_f32_16x16x32_bf16 v[26:29], v[114:117], v[186:189], v[26:29]
	v_mfma_f32_16x16x32_bf16 v[14:17], v[78:81], v[190:193], v[14:17]
	v_mfma_f32_16x16x32_bf16 v[14:17], v[90:93], v[214:217], v[14:17]
	v_mfma_f32_16x16x32_bf16 v[10:13], v[102:105], v[190:193], v[10:13]
	v_mfma_f32_16x16x32_bf16 v[10:13], v[114:117], v[214:217], v[10:13]
	s_setprio 0
	s_setprio 1
	v_mfma_f32_16x16x32_bf16 v[54:57], v[126:129], v[158:161], v[54:57]
	v_mfma_f32_16x16x32_bf16 v[54:57], v[134:137], v[162:165], v[54:57]
	v_mfma_f32_16x16x32_bf16 v[50:53], v[142:145], v[158:161], v[50:53]
	v_mfma_f32_16x16x32_bf16 v[50:53], v[154:157], v[162:165], v[50:53]
	v_mfma_f32_16x16x32_bf16 v[38:41], v[126:129], v[166:169], v[38:41]
	v_mfma_f32_16x16x32_bf16 v[38:41], v[134:137], v[178:181], v[38:41]
	v_mfma_f32_16x16x32_bf16 v[34:37], v[142:145], v[166:169], v[34:37]
	v_mfma_f32_16x16x32_bf16 v[34:37], v[154:157], v[178:181], v[34:37]
	v_mfma_f32_16x16x32_bf16 v[22:25], v[126:129], v[182:185], v[22:25]
	v_mfma_f32_16x16x32_bf16 v[22:25], v[134:137], v[186:189], v[22:25]
	v_mfma_f32_16x16x32_bf16 v[18:21], v[142:145], v[182:185], v[18:21]
	v_mfma_f32_16x16x32_bf16 v[18:21], v[154:157], v[186:189], v[18:21]
	v_mfma_f32_16x16x32_bf16 v[6:9], v[126:129], v[190:193], v[6:9]
	v_mfma_f32_16x16x32_bf16 v[6:9], v[134:137], v[214:217], v[6:9]
	v_mfma_f32_16x16x32_bf16 v[2:5], v[142:145], v[190:193], v[2:5]
	v_mfma_f32_16x16x32_bf16 v[2:5], v[154:157], v[214:217], v[2:5]
	s_setprio 0
	s_barrier
	s_add_i32 s57, s57, 2
	s_add_u32 s51, s51, 0x100
	s_addc_u32 s53, s53, 0
	s_cmp_gt_u32 s57, 29
	s_mov_b64 s[76:77], s[90:91]
	s_cbranch_scc1 .LBB0_512

.LBB0_581:
	s_add_u32 s18, s62, 0xfff80080
	s_addc_u32 s19, s63, -1
	s_and_b64 s[0:1], s[64:65], exec
	s_cselect_b32 s71, s22, s19
	s_cselect_b32 s70, s23, s18
	s_cselect_b32 s65, s39, s58
	s_cselect_b32 s64, s47, s53
	s_add_i32 s0, 0, 0x10000
	v_add_u32_e32 v153, s0, v1
	s_add_i32 s18, 0, 0x14000
	ds_read_b128 v[144:147], v153
	ds_read_b128 v[148:151], v153 offset:1024
	ds_read_b128 v[154:157], v153 offset:2048
	ds_read_b128 v[158:161], v153 offset:3072
	v_add_u32_e32 v153, s18, v1
	ds_read_b128 v[162:165], v153
	ds_read_b128 v[166:169], v153 offset:1024
	ds_read_b128 v[170:173], v153 offset:2048
	ds_read_b128 v[174:177], v153 offset:3072
	v_lshl_add_u64 v[220:221], s[62:63], 0, v[136:137]
	s_add_i32 m0, s29, 0xc000
	ds_read_b128 v[178:181], v152
	ds_read_b128 v[182:185], v152 offset:1024
	ds_read_b128 v[186:189], v152 offset:2048
	ds_read_b128 v[190:193], v152 offset:3072
	ds_read_b128 v[204:207], v152 offset:4096
	ds_read_b128 v[208:211], v152 offset:5120
	ds_read_b128 v[212:215], v152 offset:6144
	ds_read_b128 v[216:219], v152 offset:7168
	global_load_lds_dwordx4 v[220:221], off
	v_lshl_add_u64 v[220:221], s[62:63], 0, v[138:139]
	s_add_i32 m0, s29, 0xe000
	s_nop 0
	global_load_lds_dwordx4 v[220:221], off
	s_waitcnt vmcnt(8)
	s_waitcnt lgkmcnt(0)
	s_barrier
	s_setprio 1
	s_waitcnt lgkmcnt(0)
	v_mfma_f32_16x16x32_bf16 v[126:129], v[144:147], v[178:181], v[126:129]
	v_mfma_f32_16x16x32_bf16 v[126:129], v[148:151], v[182:185], v[126:129]
	v_mfma_f32_16x16x32_bf16 v[122:125], v[154:157], v[178:181], v[122:125]
	v_mfma_f32_16x16x32_bf16 v[122:125], v[158:161], v[182:185], v[122:125]
	v_mfma_f32_16x16x32_bf16 v[110:113], v[144:147], v[186:189], v[110:113]
	v_mfma_f32_16x16x32_bf16 v[110:113], v[148:151], v[190:193], v[110:113]
	v_mfma_f32_16x16x32_bf16 v[106:109], v[154:157], v[186:189], v[106:109]
	v_mfma_f32_16x16x32_bf16 v[106:109], v[158:161], v[190:193], v[106:109]
	v_mfma_f32_16x16x32_bf16 v[94:97], v[144:147], v[204:207], v[94:97]
	v_mfma_f32_16x16x32_bf16 v[94:97], v[148:151], v[208:211], v[94:97]
	v_mfma_f32_16x16x32_bf16 v[90:93], v[154:157], v[204:207], v[90:93]
	v_mfma_f32_16x16x32_bf16 v[90:93], v[158:161], v[208:211], v[90:93]
	v_mfma_f32_16x16x32_bf16 v[78:81], v[144:147], v[212:215], v[78:81]
	v_mfma_f32_16x16x32_bf16 v[78:81], v[148:151], v[216:219], v[78:81]
	v_mfma_f32_16x16x32_bf16 v[74:77], v[154:157], v[212:215], v[74:77]
	v_mfma_f32_16x16x32_bf16 v[74:77], v[158:161], v[216:219], v[74:77]
	s_setprio 0
	s_setprio 1
	v_mfma_f32_16x16x32_bf16 v[118:121], v[162:165], v[178:181], v[118:121]
	v_mfma_f32_16x16x32_bf16 v[118:121], v[166:169], v[182:185], v[118:121]
	v_mfma_f32_16x16x32_bf16 v[114:117], v[170:173], v[178:181], v[114:117]
	v_mfma_f32_16x16x32_bf16 v[114:117], v[174:177], v[182:185], v[114:117]
	v_mfma_f32_16x16x32_bf16 v[102:105], v[162:165], v[186:189], v[102:105]
	v_mfma_f32_16x16x32_bf16 v[102:105], v[166:169], v[190:193], v[102:105]
	v_mfma_f32_16x16x32_bf16 v[98:101], v[170:173], v[186:189], v[98:101]
	v_mfma_f32_16x16x32_bf16 v[98:101], v[174:177], v[190:193], v[98:101]
	v_mfma_f32_16x16x32_bf16 v[86:89], v[162:165], v[204:207], v[86:89]
	v_mfma_f32_16x16x32_bf16 v[86:89], v[166:169], v[208:211], v[86:89]
	v_mfma_f32_16x16x32_bf16 v[82:85], v[170:173], v[204:207], v[82:85]
	v_mfma_f32_16x16x32_bf16 v[82:85], v[174:177], v[208:211], v[82:85]
	v_mfma_f32_16x16x32_bf16 v[70:73], v[162:165], v[212:215], v[70:73]
	v_mfma_f32_16x16x32_bf16 v[70:73], v[166:169], v[216:219], v[70:73]
	v_mfma_f32_16x16x32_bf16 v[66:69], v[170:173], v[212:215], v[66:69]
	v_mfma_f32_16x16x32_bf16 v[66:69], v[174:177], v[216:219], v[66:69]
	s_setprio 0
	s_barrier
	s_add_i32 s0, s0, s28
	v_lshl_add_u64 v[220:221], s[64:65], 0, v[194:195]
	s_mov_b32 m0, s0
	ds_read_b128 v[178:181], v152 offset:16384
	ds_read_b128 v[182:185], v152 offset:17408
	ds_read_b128 v[186:189], v152 offset:18432
	ds_read_b128 v[190:193], v152 offset:19456
	ds_read_b128 v[204:207], v152 offset:20480
	ds_read_b128 v[208:211], v152 offset:21504
	ds_read_b128 v[212:215], v152 offset:22528
	ds_read_b128 v[216:219], v152 offset:23552
	global_load_lds_dwordx4 v[220:221], off
	s_add_i32 m0, s0, 0x2000
	s_add_u32 s0, s64, 0x80000
	v_lshl_add_u64 v[222:223], s[64:65], 0, v[130:131]
	s_addc_u32 s1, s65, 0
	s_add_i32 s18, s18, s28
	global_load_lds_dwordx4 v[222:223], off
	v_lshl_add_u64 v[224:225], s[0:1], 0, v[194:195]
	s_mov_b32 m0, s18
	v_lshl_add_u64 v[226:227], s[70:71], 0, v[130:131]
	global_load_lds_dwordx4 v[224:225], off
	v_lshl_add_u64 v[224:225], s[0:1], 0, v[130:131]
	s_add_i32 m0, s18, 0x2000
	s_nop 0
	global_load_lds_dwordx4 v[224:225], off
	v_lshl_add_u64 v[224:225], s[70:71], 0, v[194:195]
	s_mov_b32 m0, s29
	s_nop 0
	global_load_lds_dwordx4 v[224:225], off
	s_mov_b32 m0, s31
	s_nop 0
	global_load_lds_dwordx4 v[226:227], off
	s_waitcnt vmcnt(8)
	s_waitcnt lgkmcnt(0)
	s_barrier
	s_setprio 1
	s_waitcnt lgkmcnt(0)
	v_mfma_f32_16x16x32_bf16 v[62:65], v[144:147], v[178:181], v[62:65]
	v_mfma_f32_16x16x32_bf16 v[62:65], v[148:151], v[182:185], v[62:65]
	v_mfma_f32_16x16x32_bf16 v[58:61], v[154:157], v[178:181], v[58:61]
	v_mfma_f32_16x16x32_bf16 v[58:61], v[158:161], v[182:185], v[58:61]
	v_mfma_f32_16x16x32_bf16 v[46:49], v[144:147], v[186:189], v[46:49]
	v_mfma_f32_16x16x32_bf16 v[46:49], v[148:151], v[190:193], v[46:49]
	v_mfma_f32_16x16x32_bf16 v[42:45], v[154:157], v[186:189], v[42:45]
	v_mfma_f32_16x16x32_bf16 v[42:45], v[158:161], v[190:193], v[42:45]
	v_mfma_f32_16x16x32_bf16 v[30:33], v[144:147], v[204:207], v[30:33]
	v_mfma_f32_16x16x32_bf16 v[30:33], v[148:151], v[208:211], v[30:33]
	v_mfma_f32_16x16x32_bf16 v[26:29], v[154:157], v[204:207], v[26:29]
	v_mfma_f32_16x16x32_bf16 v[26:29], v[158:161], v[208:211], v[26:29]
	v_mfma_f32_16x16x32_bf16 v[14:17], v[144:147], v[212:215], v[14:17]
	v_mfma_f32_16x16x32_bf16 v[14:17], v[148:151], v[216:219], v[14:17]
	v_mfma_f32_16x16x32_bf16 v[10:13], v[154:157], v[212:215], v[10:13]
	v_mfma_f32_16x16x32_bf16 v[10:13], v[158:161], v[216:219], v[10:13]
	s_setprio 0
	s_setprio 1
	v_mfma_f32_16x16x32_bf16 v[54:57], v[162:165], v[178:181], v[54:57]
	v_mfma_f32_16x16x32_bf16 v[54:57], v[166:169], v[182:185], v[54:57]
	v_mfma_f32_16x16x32_bf16 v[50:53], v[170:173], v[178:181], v[50:53]
	v_mfma_f32_16x16x32_bf16 v[50:53], v[174:177], v[182:185], v[50:53]
	v_mfma_f32_16x16x32_bf16 v[38:41], v[162:165], v[186:189], v[38:41]
	v_mfma_f32_16x16x32_bf16 v[38:41], v[166:169], v[190:193], v[38:41]
	v_mfma_f32_16x16x32_bf16 v[34:37], v[170:173], v[186:189], v[34:37]
	v_mfma_f32_16x16x32_bf16 v[34:37], v[174:177], v[190:193], v[34:37]
	v_mfma_f32_16x16x32_bf16 v[22:25], v[162:165], v[204:207], v[22:25]
	v_mfma_f32_16x16x32_bf16 v[22:25], v[166:169], v[208:211], v[22:25]
	v_mfma_f32_16x16x32_bf16 v[18:21], v[170:173], v[204:207], v[18:21]
	v_mfma_f32_16x16x32_bf16 v[18:21], v[174:177], v[208:211], v[18:21]
	v_mfma_f32_16x16x32_bf16 v[6:9], v[162:165], v[212:215], v[6:9]
	v_mfma_f32_16x16x32_bf16 v[6:9], v[166:169], v[216:219], v[6:9]
	v_mfma_f32_16x16x32_bf16 v[2:5], v[170:173], v[212:215], v[2:5]
	v_mfma_f32_16x16x32_bf16 v[2:5], v[174:177], v[216:219], v[2:5]
	s_setprio 0
	s_barrier
	s_add_i32 s18, 0, 0x18000
	v_add_u32_e32 v153, s18, v1
	s_add_i32 s19, 0, 0x1c000
	ds_read_b128 v[144:147], v153
	ds_read_b128 v[148:151], v153 offset:1024
	ds_read_b128 v[154:157], v153 offset:2048
	ds_read_b128 v[158:161], v153 offset:3072
	v_add_u32_e32 v153, s19, v1
	ds_read_b128 v[162:165], v153
	ds_read_b128 v[166:169], v153 offset:1024
	ds_read_b128 v[170:173], v153 offset:2048
	ds_read_b128 v[174:177], v153 offset:3072
	s_add_u32 s0, s70, 0x80000
	s_addc_u32 s1, s71, 0
	s_mov_b32 m0, s33
	v_lshl_add_u64 v[228:229], s[0:1], 0, v[194:195]
	ds_read_b128 v[178:181], v152 offset:32768
	ds_read_b128 v[182:185], v152 offset:33792
	ds_read_b128 v[186:189], v152 offset:34816
	ds_read_b128 v[190:193], v152 offset:35840
	ds_read_b128 v[204:207], v152 offset:36864
	ds_read_b128 v[208:211], v152 offset:37888
	ds_read_b128 v[212:215], v152 offset:38912
	ds_read_b128 v[216:219], v152 offset:39936
	global_load_lds_dwordx4 v[228:229], off
	v_lshl_add_u64 v[228:229], s[0:1], 0, v[130:131]
	s_mov_b32 m0, s40
	s_nop 0
	global_load_lds_dwordx4 v[228:229], off
	s_waitcnt vmcnt(8)
	s_waitcnt lgkmcnt(0)
	s_barrier
	s_setprio 1
	s_waitcnt lgkmcnt(0)
	v_mfma_f32_16x16x32_bf16 v[126:129], v[144:147], v[178:181], v[126:129]
	v_mfma_f32_16x16x32_bf16 v[126:129], v[148:151], v[182:185], v[126:129]
	v_mfma_f32_16x16x32_bf16 v[122:125], v[154:157], v[178:181], v[122:125]
	v_mfma_f32_16x16x32_bf16 v[122:125], v[158:161], v[182:185], v[122:125]
	v_mfma_f32_16x16x32_bf16 v[110:113], v[144:147], v[186:189], v[110:113]
	v_mfma_f32_16x16x32_bf16 v[110:113], v[148:151], v[190:193], v[110:113]
	v_mfma_f32_16x16x32_bf16 v[106:109], v[154:157], v[186:189], v[106:109]
	v_mfma_f32_16x16x32_bf16 v[106:109], v[158:161], v[190:193], v[106:109]
	v_mfma_f32_16x16x32_bf16 v[94:97], v[144:147], v[204:207], v[94:97]
	v_mfma_f32_16x16x32_bf16 v[94:97], v[148:151], v[208:211], v[94:97]
	v_mfma_f32_16x16x32_bf16 v[90:93], v[154:157], v[204:207], v[90:93]
	v_mfma_f32_16x16x32_bf16 v[90:93], v[158:161], v[208:211], v[90:93]
	v_mfma_f32_16x16x32_bf16 v[78:81], v[144:147], v[212:215], v[78:81]
	v_mfma_f32_16x16x32_bf16 v[78:81], v[148:151], v[216:219], v[78:81]
	v_mfma_f32_16x16x32_bf16 v[74:77], v[154:157], v[212:215], v[74:77]
	v_mfma_f32_16x16x32_bf16 v[74:77], v[158:161], v[216:219], v[74:77]
	s_setprio 0
	s_setprio 1
	v_mfma_f32_16x16x32_bf16 v[118:121], v[162:165], v[178:181], v[118:121]
	v_mfma_f32_16x16x32_bf16 v[118:121], v[166:169], v[182:185], v[118:121]
	v_mfma_f32_16x16x32_bf16 v[114:117], v[170:173], v[178:181], v[114:117]
	v_mfma_f32_16x16x32_bf16 v[114:117], v[174:177], v[182:185], v[114:117]
	v_mfma_f32_16x16x32_bf16 v[102:105], v[162:165], v[186:189], v[102:105]
	v_mfma_f32_16x16x32_bf16 v[102:105], v[166:169], v[190:193], v[102:105]
	v_mfma_f32_16x16x32_bf16 v[98:101], v[170:173], v[186:189], v[98:101]
	v_mfma_f32_16x16x32_bf16 v[98:101], v[174:177], v[190:193], v[98:101]
	v_mfma_f32_16x16x32_bf16 v[86:89], v[162:165], v[204:207], v[86:89]
	v_mfma_f32_16x16x32_bf16 v[86:89], v[166:169], v[208:211], v[86:89]
	v_mfma_f32_16x16x32_bf16 v[82:85], v[170:173], v[204:207], v[82:85]
	v_mfma_f32_16x16x32_bf16 v[82:85], v[174:177], v[208:211], v[82:85]
	v_mfma_f32_16x16x32_bf16 v[70:73], v[162:165], v[212:215], v[70:73]
	v_mfma_f32_16x16x32_bf16 v[70:73], v[166:169], v[216:219], v[70:73]
	v_mfma_f32_16x16x32_bf16 v[66:69], v[170:173], v[212:215], v[66:69]
	v_mfma_f32_16x16x32_bf16 v[66:69], v[174:177], v[216:219], v[66:69]
	s_setprio 0
	s_barrier
	s_add_i32 s0, s18, s28
	v_lshl_add_u64 v[220:221], v[220:221], 0, s[82:83]
	s_mov_b32 m0, s0
	ds_read_b128 v[178:181], v152 offset:49152
	ds_read_b128 v[182:185], v152 offset:50176
	ds_read_b128 v[186:189], v152 offset:51200
	ds_read_b128 v[190:193], v152 offset:52224
	ds_read_b128 v[204:207], v152 offset:53248
	ds_read_b128 v[208:211], v152 offset:54272
	ds_read_b128 v[212:215], v152 offset:55296
	ds_read_b128 v[216:219], v152 offset:56320
	global_load_lds_dwordx4 v[220:221], off
	s_add_i32 m0, s0, 0x2000
	s_add_u32 s0, s64, 0x80080
	v_lshl_add_u64 v[220:221], v[222:223], 0, s[82:83]
	s_addc_u32 s1, s65, 0
	s_add_i32 s18, s19, s28
	global_load_lds_dwordx4 v[220:221], off
	v_lshl_add_u64 v[220:221], s[0:1], 0, v[194:195]
	s_mov_b32 m0, s18
	s_nop 0
	global_load_lds_dwordx4 v[220:221], off
	v_lshl_add_u64 v[220:221], s[0:1], 0, v[130:131]
	s_add_i32 m0, s18, 0x2000
	s_nop 0
	global_load_lds_dwordx4 v[220:221], off
	v_lshl_add_u64 v[220:221], v[224:225], 0, s[82:83]
	s_mov_b32 m0, s54
	s_nop 0
	global_load_lds_dwordx4 v[220:221], off
	v_lshl_add_u64 v[220:221], v[226:227], 0, s[82:83]
	s_mov_b32 m0, s57
	s_nop 0
	global_load_lds_dwordx4 v[220:221], off
	s_waitcnt vmcnt(8)
	s_waitcnt lgkmcnt(0)
	s_barrier
	s_setprio 1
	s_waitcnt lgkmcnt(0)
	v_mfma_f32_16x16x32_bf16 v[62:65], v[144:147], v[178:181], v[62:65]
	v_mfma_f32_16x16x32_bf16 v[62:65], v[148:151], v[182:185], v[62:65]
	v_mfma_f32_16x16x32_bf16 v[58:61], v[154:157], v[178:181], v[58:61]
	v_mfma_f32_16x16x32_bf16 v[58:61], v[158:161], v[182:185], v[58:61]
	v_mfma_f32_16x16x32_bf16 v[46:49], v[144:147], v[186:189], v[46:49]
	v_mfma_f32_16x16x32_bf16 v[46:49], v[148:151], v[190:193], v[46:49]
	v_mfma_f32_16x16x32_bf16 v[42:45], v[154:157], v[186:189], v[42:45]
	v_mfma_f32_16x16x32_bf16 v[42:45], v[158:161], v[190:193], v[42:45]
	v_mfma_f32_16x16x32_bf16 v[30:33], v[144:147], v[204:207], v[30:33]
	v_mfma_f32_16x16x32_bf16 v[30:33], v[148:151], v[208:211], v[30:33]
	v_mfma_f32_16x16x32_bf16 v[26:29], v[154:157], v[204:207], v[26:29]
	v_mfma_f32_16x16x32_bf16 v[26:29], v[158:161], v[208:211], v[26:29]
	v_mfma_f32_16x16x32_bf16 v[14:17], v[144:147], v[212:215], v[14:17]
	v_mfma_f32_16x16x32_bf16 v[14:17], v[148:151], v[216:219], v[14:17]
	v_mfma_f32_16x16x32_bf16 v[10:13], v[154:157], v[212:215], v[10:13]
	v_mfma_f32_16x16x32_bf16 v[10:13], v[158:161], v[216:219], v[10:13]
	s_setprio 0
	s_setprio 1
	v_mfma_f32_16x16x32_bf16 v[54:57], v[162:165], v[178:181], v[54:57]
	v_mfma_f32_16x16x32_bf16 v[54:57], v[166:169], v[182:185], v[54:57]
	v_mfma_f32_16x16x32_bf16 v[50:53], v[170:173], v[178:181], v[50:53]
	v_mfma_f32_16x16x32_bf16 v[50:53], v[174:177], v[182:185], v[50:53]
	v_mfma_f32_16x16x32_bf16 v[38:41], v[162:165], v[186:189], v[38:41]
	v_mfma_f32_16x16x32_bf16 v[38:41], v[166:169], v[190:193], v[38:41]
	v_mfma_f32_16x16x32_bf16 v[34:37], v[170:173], v[186:189], v[34:37]
	v_mfma_f32_16x16x32_bf16 v[34:37], v[174:177], v[190:193], v[34:37]
	v_mfma_f32_16x16x32_bf16 v[22:25], v[162:165], v[204:207], v[22:25]
	v_mfma_f32_16x16x32_bf16 v[22:25], v[166:169], v[208:211], v[22:25]
	v_mfma_f32_16x16x32_bf16 v[18:21], v[170:173], v[204:207], v[18:21]
	v_mfma_f32_16x16x32_bf16 v[18:21], v[174:177], v[208:211], v[18:21]
	v_mfma_f32_16x16x32_bf16 v[6:9], v[162:165], v[212:215], v[6:9]
	v_mfma_f32_16x16x32_bf16 v[6:9], v[166:169], v[216:219], v[6:9]
	v_mfma_f32_16x16x32_bf16 v[2:5], v[170:173], v[212:215], v[2:5]
	v_mfma_f32_16x16x32_bf16 v[2:5], v[174:177], v[216:219], v[2:5]
	s_setprio 0
	s_barrier
	s_add_i32 s76, s76, 2
	s_add_u32 s62, s62, 0x100
	s_addc_u32 s63, s63, 0
	s_add_u32 s53, s53, 0x100
	s_addc_u32 s58, s58, 0
	s_cmp_gt_u32 s76, 29
	s_cbranch_scc1 .LBB0_584

.LBB0_645:
	s_add_u32 s64, s8, 0x100
	s_addc_u32 s65, s9, 0
	s_and_b64 s[0:1], s[70:71], exec
	s_cselect_b32 s77, s63, s65
	s_cselect_b32 s76, s62, s64
	s_cselect_b32 s71, s85, s23
	s_cselect_b32 s70, s84, s7
	s_add_i32 s0, 0, 0x10000
	s_add_i32 s18, 0, 0x14000
	v_add_u32_e32 v106, s0, v1
	v_add_u32_e32 v154, s18, v1
	ds_read_b128 v[70:73], v106
	ds_read_b128 v[82:85], v106 offset:1024
	ds_read_b128 v[94:97], v106 offset:2048
	ds_read_b128 v[106:109], v106 offset:3072
	ds_read_b128 v[118:121], v154
	ds_read_b128 v[130:133], v154 offset:1024
	ds_read_b128 v[142:145], v154 offset:2048
	ds_read_b128 v[154:157], v154 offset:3072
	v_lshl_add_u64 v[218:219], s[8:9], 0, v[206:207]
	s_add_i32 m0, s29, 0xc000
	ds_read_b128 v[158:161], v237
	ds_read_b128 v[170:173], v237 offset:1024
	ds_read_b128 v[174:177], v237 offset:2048
	ds_read_b128 v[178:181], v237 offset:3072
	ds_read_b128 v[182:185], v237 offset:4096
	ds_read_b128 v[186:189], v237 offset:5120
	ds_read_b128 v[210:213], v237 offset:6144
	ds_read_b128 v[214:217], v237 offset:7168
	global_load_lds_dwordx4 v[218:219], off
	v_lshl_add_u64 v[218:219], s[8:9], 0, v[208:209]
	s_add_i32 m0, s29, 0xe000
	s_nop 0
	global_load_lds_dwordx4 v[218:219], off
	s_waitcnt vmcnt(8)
	s_waitcnt lgkmcnt(0)
	s_barrier
	s_setprio 1
	s_waitcnt lgkmcnt(0)
	v_mfma_f32_16x16x32_bf16 v[166:169], v[70:73], v[158:161], v[166:169]
	v_mfma_f32_16x16x32_bf16 v[166:169], v[82:85], v[170:173], v[166:169]
	v_mfma_f32_16x16x32_bf16 v[162:165], v[94:97], v[158:161], v[162:165]
	v_mfma_f32_16x16x32_bf16 v[162:165], v[106:109], v[170:173], v[162:165]
	v_mfma_f32_16x16x32_bf16 v[138:141], v[70:73], v[174:177], v[138:141]
	v_mfma_f32_16x16x32_bf16 v[138:141], v[82:85], v[178:181], v[138:141]
	v_mfma_f32_16x16x32_bf16 v[134:137], v[94:97], v[174:177], v[134:137]
	v_mfma_f32_16x16x32_bf16 v[134:137], v[106:109], v[178:181], v[134:137]
	v_mfma_f32_16x16x32_bf16 v[114:117], v[70:73], v[182:185], v[114:117]
	v_mfma_f32_16x16x32_bf16 v[114:117], v[82:85], v[186:189], v[114:117]
	v_mfma_f32_16x16x32_bf16 v[110:113], v[94:97], v[182:185], v[110:113]
	v_mfma_f32_16x16x32_bf16 v[110:113], v[106:109], v[186:189], v[110:113]
	v_mfma_f32_16x16x32_bf16 v[90:93], v[70:73], v[210:213], v[90:93]
	v_mfma_f32_16x16x32_bf16 v[90:93], v[82:85], v[214:217], v[90:93]
	v_mfma_f32_16x16x32_bf16 v[86:89], v[94:97], v[210:213], v[86:89]
	v_mfma_f32_16x16x32_bf16 v[86:89], v[106:109], v[214:217], v[86:89]
	s_setprio 0
	s_setprio 1
	v_mfma_f32_16x16x32_bf16 v[150:153], v[118:121], v[158:161], v[150:153]
	v_mfma_f32_16x16x32_bf16 v[150:153], v[130:133], v[170:173], v[150:153]
	v_mfma_f32_16x16x32_bf16 v[146:149], v[142:145], v[158:161], v[146:149]
	v_mfma_f32_16x16x32_bf16 v[146:149], v[154:157], v[170:173], v[146:149]
	v_mfma_f32_16x16x32_bf16 v[126:129], v[118:121], v[174:177], v[126:129]
	v_mfma_f32_16x16x32_bf16 v[126:129], v[130:133], v[178:181], v[126:129]
	v_mfma_f32_16x16x32_bf16 v[122:125], v[142:145], v[174:177], v[122:125]
	v_mfma_f32_16x16x32_bf16 v[122:125], v[154:157], v[178:181], v[122:125]
	v_mfma_f32_16x16x32_bf16 v[102:105], v[118:121], v[182:185], v[102:105]
	v_mfma_f32_16x16x32_bf16 v[102:105], v[130:133], v[186:189], v[102:105]
	v_mfma_f32_16x16x32_bf16 v[98:101], v[142:145], v[182:185], v[98:101]
	v_mfma_f32_16x16x32_bf16 v[98:101], v[154:157], v[186:189], v[98:101]
	v_mfma_f32_16x16x32_bf16 v[78:81], v[118:121], v[210:213], v[78:81]
	v_mfma_f32_16x16x32_bf16 v[78:81], v[130:133], v[214:217], v[78:81]
	v_mfma_f32_16x16x32_bf16 v[74:77], v[142:145], v[210:213], v[74:77]
	v_mfma_f32_16x16x32_bf16 v[74:77], v[154:157], v[214:217], v[74:77]
	s_setprio 0
	s_barrier
	s_add_i32 s0, s0, s28
	v_lshl_add_u64 v[218:219], s[70:71], 0, v[192:193]
	s_mov_b32 m0, s0
	ds_read_b128 v[158:161], v237 offset:16384
	ds_read_b128 v[170:173], v237 offset:17408
	ds_read_b128 v[174:177], v237 offset:18432
	ds_read_b128 v[178:181], v237 offset:19456
	ds_read_b128 v[182:185], v237 offset:20480
	ds_read_b128 v[186:189], v237 offset:21504
	ds_read_b128 v[210:213], v237 offset:22528
	ds_read_b128 v[214:217], v237 offset:23552
	global_load_lds_dwordx4 v[218:219], off
	s_add_i32 m0, s0, 0x2000
	s_add_u32 s0, s70, 0x160000
	v_lshl_add_u64 v[220:221], s[70:71], 0, v[190:191]
	s_addc_u32 s1, s71, 0
	s_add_i32 s8, s18, s28
	global_load_lds_dwordx4 v[220:221], off
	v_lshl_add_u64 v[222:223], s[0:1], 0, v[192:193]
	s_mov_b32 m0, s8
	v_lshl_add_u64 v[224:225], s[76:77], 0, v[190:191]
	global_load_lds_dwordx4 v[222:223], off
	v_lshl_add_u64 v[222:223], s[0:1], 0, v[190:191]
	s_add_i32 m0, s8, 0x2000
	s_nop 0
	global_load_lds_dwordx4 v[222:223], off
	v_lshl_add_u64 v[222:223], s[76:77], 0, v[192:193]
	s_mov_b32 m0, s29
	s_nop 0
	global_load_lds_dwordx4 v[222:223], off
	s_mov_b32 m0, s31
	s_nop 0
	global_load_lds_dwordx4 v[224:225], off
	s_waitcnt vmcnt(8)
	s_waitcnt lgkmcnt(0)
	s_barrier
	s_setprio 1
	s_waitcnt lgkmcnt(0)
	v_mfma_f32_16x16x32_bf16 v[62:65], v[70:73], v[158:161], v[62:65]
	v_mfma_f32_16x16x32_bf16 v[62:65], v[82:85], v[170:173], v[62:65]
	v_mfma_f32_16x16x32_bf16 v[58:61], v[94:97], v[158:161], v[58:61]
	v_mfma_f32_16x16x32_bf16 v[58:61], v[106:109], v[170:173], v[58:61]
	v_mfma_f32_16x16x32_bf16 v[46:49], v[70:73], v[174:177], v[46:49]
	v_mfma_f32_16x16x32_bf16 v[46:49], v[82:85], v[178:181], v[46:49]
	v_mfma_f32_16x16x32_bf16 v[42:45], v[94:97], v[174:177], v[42:45]
	v_mfma_f32_16x16x32_bf16 v[42:45], v[106:109], v[178:181], v[42:45]
	v_mfma_f32_16x16x32_bf16 v[30:33], v[70:73], v[182:185], v[30:33]
	v_mfma_f32_16x16x32_bf16 v[30:33], v[82:85], v[186:189], v[30:33]
	v_mfma_f32_16x16x32_bf16 v[26:29], v[94:97], v[182:185], v[26:29]
	v_mfma_f32_16x16x32_bf16 v[26:29], v[106:109], v[186:189], v[26:29]
	v_mfma_f32_16x16x32_bf16 v[14:17], v[70:73], v[210:213], v[14:17]
	v_mfma_f32_16x16x32_bf16 v[14:17], v[82:85], v[214:217], v[14:17]
	v_mfma_f32_16x16x32_bf16 v[10:13], v[94:97], v[210:213], v[10:13]
	v_mfma_f32_16x16x32_bf16 v[10:13], v[106:109], v[214:217], v[10:13]
	s_setprio 0
	s_setprio 1
	v_mfma_f32_16x16x32_bf16 v[54:57], v[118:121], v[158:161], v[54:57]
	v_mfma_f32_16x16x32_bf16 v[54:57], v[130:133], v[170:173], v[54:57]
	v_mfma_f32_16x16x32_bf16 v[50:53], v[142:145], v[158:161], v[50:53]
	v_mfma_f32_16x16x32_bf16 v[50:53], v[154:157], v[170:173], v[50:53]
	v_mfma_f32_16x16x32_bf16 v[38:41], v[118:121], v[174:177], v[38:41]
	v_mfma_f32_16x16x32_bf16 v[38:41], v[130:133], v[178:181], v[38:41]
	v_mfma_f32_16x16x32_bf16 v[34:37], v[142:145], v[174:177], v[34:37]
	v_mfma_f32_16x16x32_bf16 v[34:37], v[154:157], v[178:181], v[34:37]
	v_mfma_f32_16x16x32_bf16 v[22:25], v[118:121], v[182:185], v[22:25]
	v_mfma_f32_16x16x32_bf16 v[22:25], v[130:133], v[186:189], v[22:25]
	v_mfma_f32_16x16x32_bf16 v[18:21], v[142:145], v[182:185], v[18:21]
	v_mfma_f32_16x16x32_bf16 v[18:21], v[154:157], v[186:189], v[18:21]
	v_mfma_f32_16x16x32_bf16 v[6:9], v[118:121], v[210:213], v[6:9]
	v_mfma_f32_16x16x32_bf16 v[6:9], v[130:133], v[214:217], v[6:9]
	v_mfma_f32_16x16x32_bf16 v[2:5], v[142:145], v[210:213], v[2:5]
	v_mfma_f32_16x16x32_bf16 v[2:5], v[154:157], v[214:217], v[2:5]
	s_setprio 0
	s_barrier
	s_add_i32 s8, 0, 0x18000
	s_add_i32 s9, 0, 0x1c000
	v_add_u32_e32 v106, s8, v1
	v_add_u32_e32 v154, s9, v1
	ds_read_b128 v[70:73], v106
	ds_read_b128 v[82:85], v106 offset:1024
	ds_read_b128 v[94:97], v106 offset:2048
	ds_read_b128 v[106:109], v106 offset:3072
	ds_read_b128 v[118:121], v154
	ds_read_b128 v[130:133], v154 offset:1024
	ds_read_b128 v[142:145], v154 offset:2048
	ds_read_b128 v[154:157], v154 offset:3072
	s_add_u32 s0, s76, 0x160000
	s_addc_u32 s1, s77, 0
	s_mov_b32 m0, s33
	v_lshl_add_u64 v[226:227], s[0:1], 0, v[192:193]
	ds_read_b128 v[158:161], v237 offset:32768
	ds_read_b128 v[170:173], v237 offset:33792
	ds_read_b128 v[174:177], v237 offset:34816
	ds_read_b128 v[178:181], v237 offset:35840
	ds_read_b128 v[182:185], v237 offset:36864
	ds_read_b128 v[186:189], v237 offset:37888
	ds_read_b128 v[210:213], v237 offset:38912
	ds_read_b128 v[214:217], v237 offset:39936
	global_load_lds_dwordx4 v[226:227], off
	v_lshl_add_u64 v[226:227], s[0:1], 0, v[190:191]
	s_mov_b32 m0, s43
	s_nop 0
	global_load_lds_dwordx4 v[226:227], off
	s_waitcnt vmcnt(8)
	s_waitcnt lgkmcnt(0)
	s_barrier
	s_setprio 1
	s_waitcnt lgkmcnt(0)
	v_mfma_f32_16x16x32_bf16 v[166:169], v[70:73], v[158:161], v[166:169]
	v_mfma_f32_16x16x32_bf16 v[166:169], v[82:85], v[170:173], v[166:169]
	v_mfma_f32_16x16x32_bf16 v[162:165], v[94:97], v[158:161], v[162:165]
	v_mfma_f32_16x16x32_bf16 v[162:165], v[106:109], v[170:173], v[162:165]
	v_mfma_f32_16x16x32_bf16 v[138:141], v[70:73], v[174:177], v[138:141]
	v_mfma_f32_16x16x32_bf16 v[138:141], v[82:85], v[178:181], v[138:141]
	v_mfma_f32_16x16x32_bf16 v[134:137], v[94:97], v[174:177], v[134:137]
	v_mfma_f32_16x16x32_bf16 v[134:137], v[106:109], v[178:181], v[134:137]
	v_mfma_f32_16x16x32_bf16 v[114:117], v[70:73], v[182:185], v[114:117]
	v_mfma_f32_16x16x32_bf16 v[114:117], v[82:85], v[186:189], v[114:117]
	v_mfma_f32_16x16x32_bf16 v[110:113], v[94:97], v[182:185], v[110:113]
	v_mfma_f32_16x16x32_bf16 v[110:113], v[106:109], v[186:189], v[110:113]
	v_mfma_f32_16x16x32_bf16 v[90:93], v[70:73], v[210:213], v[90:93]
	v_mfma_f32_16x16x32_bf16 v[90:93], v[82:85], v[214:217], v[90:93]
	v_mfma_f32_16x16x32_bf16 v[86:89], v[94:97], v[210:213], v[86:89]
	v_mfma_f32_16x16x32_bf16 v[86:89], v[106:109], v[214:217], v[86:89]
	s_setprio 0
	s_setprio 1
	v_mfma_f32_16x16x32_bf16 v[150:153], v[118:121], v[158:161], v[150:153]
	v_mfma_f32_16x16x32_bf16 v[150:153], v[130:133], v[170:173], v[150:153]
	v_mfma_f32_16x16x32_bf16 v[146:149], v[142:145], v[158:161], v[146:149]
	v_mfma_f32_16x16x32_bf16 v[146:149], v[154:157], v[170:173], v[146:149]
	v_mfma_f32_16x16x32_bf16 v[126:129], v[118:121], v[174:177], v[126:129]
	v_mfma_f32_16x16x32_bf16 v[126:129], v[130:133], v[178:181], v[126:129]
	v_mfma_f32_16x16x32_bf16 v[122:125], v[142:145], v[174:177], v[122:125]
	v_mfma_f32_16x16x32_bf16 v[122:125], v[154:157], v[178:181], v[122:125]
	v_mfma_f32_16x16x32_bf16 v[102:105], v[118:121], v[182:185], v[102:105]
	v_mfma_f32_16x16x32_bf16 v[102:105], v[130:133], v[186:189], v[102:105]
	v_mfma_f32_16x16x32_bf16 v[98:101], v[142:145], v[182:185], v[98:101]
	v_mfma_f32_16x16x32_bf16 v[98:101], v[154:157], v[186:189], v[98:101]
	v_mfma_f32_16x16x32_bf16 v[78:81], v[118:121], v[210:213], v[78:81]
	v_mfma_f32_16x16x32_bf16 v[78:81], v[130:133], v[214:217], v[78:81]
	v_mfma_f32_16x16x32_bf16 v[74:77], v[142:145], v[210:213], v[74:77]
	v_mfma_f32_16x16x32_bf16 v[74:77], v[154:157], v[214:217], v[74:77]
	s_setprio 0
	s_barrier
	s_add_i32 s0, s8, s28
	v_lshl_add_u64 v[218:219], v[218:219], 0, s[82:83]
	s_mov_b32 m0, s0
	ds_read_b128 v[158:161], v237 offset:49152
	ds_read_b128 v[170:173], v237 offset:50176
	ds_read_b128 v[174:177], v237 offset:51200
	ds_read_b128 v[178:181], v237 offset:52224
	ds_read_b128 v[182:185], v237 offset:53248
	ds_read_b128 v[186:189], v237 offset:54272
	ds_read_b128 v[210:213], v237 offset:55296
	ds_read_b128 v[214:217], v237 offset:56320
	global_load_lds_dwordx4 v[218:219], off
	s_add_i32 m0, s0, 0x2000
	s_add_u32 s0, s70, 0x160080
	v_lshl_add_u64 v[218:219], v[220:221], 0, s[82:83]
	s_addc_u32 s1, s71, 0
	s_add_i32 s8, s9, s28
	global_load_lds_dwordx4 v[218:219], off
	v_lshl_add_u64 v[218:219], s[0:1], 0, v[192:193]
	s_mov_b32 m0, s8
	s_nop 0
	global_load_lds_dwordx4 v[218:219], off
	v_lshl_add_u64 v[218:219], s[0:1], 0, v[190:191]
	s_add_i32 m0, s8, 0x2000
	s_nop 0
	global_load_lds_dwordx4 v[218:219], off
	v_lshl_add_u64 v[218:219], v[222:223], 0, s[82:83]
	s_mov_b32 m0, s68
	s_nop 0
	global_load_lds_dwordx4 v[218:219], off
	v_lshl_add_u64 v[218:219], v[224:225], 0, s[82:83]
	s_mov_b32 m0, s79
	s_nop 0
	global_load_lds_dwordx4 v[218:219], off
	s_waitcnt vmcnt(8)
	s_waitcnt lgkmcnt(0)
	s_barrier
	s_setprio 1
	s_waitcnt lgkmcnt(0)
	v_mfma_f32_16x16x32_bf16 v[62:65], v[70:73], v[158:161], v[62:65]
	v_mfma_f32_16x16x32_bf16 v[62:65], v[82:85], v[170:173], v[62:65]
	v_mfma_f32_16x16x32_bf16 v[58:61], v[94:97], v[158:161], v[58:61]
	v_mfma_f32_16x16x32_bf16 v[58:61], v[106:109], v[170:173], v[58:61]
	v_mfma_f32_16x16x32_bf16 v[46:49], v[70:73], v[174:177], v[46:49]
	v_mfma_f32_16x16x32_bf16 v[46:49], v[82:85], v[178:181], v[46:49]
	v_mfma_f32_16x16x32_bf16 v[42:45], v[94:97], v[174:177], v[42:45]
	v_mfma_f32_16x16x32_bf16 v[42:45], v[106:109], v[178:181], v[42:45]
	v_mfma_f32_16x16x32_bf16 v[30:33], v[70:73], v[182:185], v[30:33]
	v_mfma_f32_16x16x32_bf16 v[30:33], v[82:85], v[186:189], v[30:33]
	v_mfma_f32_16x16x32_bf16 v[26:29], v[94:97], v[182:185], v[26:29]
	v_mfma_f32_16x16x32_bf16 v[26:29], v[106:109], v[186:189], v[26:29]
	v_mfma_f32_16x16x32_bf16 v[14:17], v[70:73], v[210:213], v[14:17]
	v_mfma_f32_16x16x32_bf16 v[14:17], v[82:85], v[214:217], v[14:17]
	v_mfma_f32_16x16x32_bf16 v[10:13], v[94:97], v[210:213], v[10:13]
	v_mfma_f32_16x16x32_bf16 v[10:13], v[106:109], v[214:217], v[10:13]
	s_setprio 0
	s_setprio 1
	v_mfma_f32_16x16x32_bf16 v[54:57], v[118:121], v[158:161], v[54:57]
	v_mfma_f32_16x16x32_bf16 v[54:57], v[130:133], v[170:173], v[54:57]
	v_mfma_f32_16x16x32_bf16 v[50:53], v[142:145], v[158:161], v[50:53]
	v_mfma_f32_16x16x32_bf16 v[50:53], v[154:157], v[170:173], v[50:53]
	v_mfma_f32_16x16x32_bf16 v[38:41], v[118:121], v[174:177], v[38:41]
	v_mfma_f32_16x16x32_bf16 v[38:41], v[130:133], v[178:181], v[38:41]
	v_mfma_f32_16x16x32_bf16 v[34:37], v[142:145], v[174:177], v[34:37]
	v_mfma_f32_16x16x32_bf16 v[34:37], v[154:157], v[178:181], v[34:37]
	v_mfma_f32_16x16x32_bf16 v[22:25], v[118:121], v[182:185], v[22:25]
	v_mfma_f32_16x16x32_bf16 v[22:25], v[130:133], v[186:189], v[22:25]
	v_mfma_f32_16x16x32_bf16 v[18:21], v[142:145], v[182:185], v[18:21]
	v_mfma_f32_16x16x32_bf16 v[18:21], v[154:157], v[186:189], v[18:21]
	v_mfma_f32_16x16x32_bf16 v[6:9], v[118:121], v[210:213], v[6:9]
	v_mfma_f32_16x16x32_bf16 v[6:9], v[130:133], v[214:217], v[6:9]
	v_mfma_f32_16x16x32_bf16 v[2:5], v[142:145], v[210:213], v[2:5]
	v_mfma_f32_16x16x32_bf16 v[2:5], v[154:157], v[214:217], v[2:5]
	s_setprio 0
	s_barrier
	s_add_i32 s41, s41, 2
	s_add_u32 s7, s7, 0x100
	s_addc_u32 s23, s23, 0
	s_cmpk_gt_u32 s41, 0x55
	s_mov_b64 s[8:9], s[64:65]
	s_cbranch_scc1 .LBB0_648
